# mla_w_in epilogue: the six norm-gain vectors loaded once per tile instead of a load+vmcnt(0) per row group (48 sites)
# speedup vs baseline: 1.0499x; 1.0012x over previous
; DEV unsigned cvt_pk_bf16(float lo, float hi) { unsigned r; asm volatile("v_cvt_pk_bf16_f32 %0, %1, %2" : "=v"(r) : "v"(lo), "v"(hi)); return r; }
;     DEV void operator()(const Acc& acc, const Unit& u, int wr, int wc, int fr, int fq, LAS unsigned char* misc) const {
;     ...
;             for (int m = 0; m < 4; ++m) { const int rl = ai * 128 + wr * 64 + m * 16 + fr, row = rt + rl; float sq = 0.f;
; #pragma unroll
;                 for (int bj = 0; bj < 2; ++bj)
; #pragma unroll
;                     for (int n = 0; n < 2; ++n) { const int c = bj * 128 + wc * 32 + n * 16 + 4 * fq; const f32x4 a = acc[ai][bj][m][n];
;                         if (isq) { sq += (a[0] * a[0] + a[1] * a[1]) + (a[2] * a[2] + a[3] * a[3]);
;                             if (row < TX) { const f32x4 g = *(const f32x4*)(gq + c); u32x2 w; w.x = cvt_pk_bf16(a[0] * g[0], a[1] * g[1]); w.y = cvt_pk_bf16(a[2] * g[2], a[3] * g[3]); *(u32x2*)(aqn + (size_t)row * 256 + c) = w; } }
;                         else if (bj == 0) { sq += (a[0] * a[0] + a[1] * a[1]) + (a[2] * a[2] + a[3] * a[3]);
;                             const f32x4 g = *(const f32x4*)(gk + c); u32x2 w; w.x = cvt_pk_bf16(a[0] * g[0], a[1] * g[1]); w.y = cvt_pk_bf16(a[2] * g[2], a[3] * g[3]); *(u32x2*)(ckvn + (size_t)row * 128 + c) = w; }
;                         else if (wc == 0) { *(f32x4*)(kpe + (size_t)row * 32 + n * 16 + 4 * fq) = a; } }
.LBB0_1475:
	v_mov_b32_e32 v154, v151
	v_mov_b32_e32 v155, v150
	s_lshl_b32 s19, s6, 8
	v_add_u32_e32 v156, s57, v154
	v_add_u32_e32 v146, s19, v156
	s_cmp_lg_u32 s18, 0
	v_ashrrev_i32_e32 v147, 31, v146
	s_cselect_b64 s[6:7], -1, 0
	v_lshlrev_b32_e32 v142, 2, v155
	v_lshlrev_b64 v[144:145], 8, v[146:147]
	v_add_u32_e32 v140, s60, v142
	v_lshlrev_b32_e32 v214, 2, v140
	global_load_dwordx4 v[190:193], v214, s[50:51]
	global_load_dwordx4 v[194:197], v214, s[50:51] offset:64
	global_load_dwordx4 v[198:201], v214, s[54:55]
	global_load_dwordx4 v[202:205], v214, s[54:55] offset:64
	global_load_dwordx4 v[206:209], v214, s[54:55] offset:512
	global_load_dwordx4 v[210:213], v214, s[54:55] offset:576
	s_waitcnt vmcnt(0)
	v_cmp_gt_i32_e64 s[8:9], s97, v146
	s_and_b64 vcc, exec, s[6:7]
	v_lshl_add_u64 v[148:149], s[68:69], 0, v[144:145]
	s_cbranch_vccz .LBB0_1479
	v_ashrrev_i32_e32 v141, 31, v140
	v_lshl_add_u64 v[144:145], v[140:141], 2, s[50:51]
	v_mov_b32_e32 v158, v190
	v_mov_b32_e32 v159, v191
	v_mov_b32_e32 v160, v192
	v_mov_b32_e32 v161, v193
	v_lshl_add_u64 v[144:145], v[140:141], 1, v[148:149]
	v_mul_f32_e32 v143, v123, v159
	v_mul_f32_e32 v159, v125, v161
	v_mul_f32_e32 v141, v122, v158
	v_mul_f32_e32 v157, v124, v160
	v_cvt_pk_bf16_f32 v158, v141, v143
	v_cvt_pk_bf16_f32 v159, v157, v159
	global_store_dwordx2 v[144:145], v[158:159], off
	v_lshlrev_b64 v[144:145], 9, v[146:147]
	s_cbranch_execz .LBB0_1480
	v_cndmask_b32_e64 v141, 0, 1, s[6:7]
	v_cmp_ne_u32_e64 s[4:5], 1, v141
	s_andn2_b64 vcc, exec, s[6:7]
	s_cbranch_vccnz .LBB0_1483
.LBB0_1478:
	v_ashrrev_i32_e32 v141, 31, v140
	v_lshl_add_u64 v[158:159], v[140:141], 2, s[50:51]
	v_mov_b32_e32 v158, v194
	v_mov_b32_e32 v159, v195
	v_mov_b32_e32 v160, v196
	v_mov_b32_e32 v161, v197
	v_lshl_add_u64 v[148:149], v[140:141], 1, v[148:149]
	v_mul_f32_e32 v143, v127, v159
	v_mul_f32_e32 v159, v129, v161
	v_mul_f32_e32 v141, v126, v158
	v_mul_f32_e32 v157, v128, v160
	v_cvt_pk_bf16_f32 v158, v141, v143
	v_cvt_pk_bf16_f32 v159, v157, v159
	global_store_dwordx2 v[148:149], v[158:159], off offset:32
	s_cbranch_execz .LBB0_1484
	s_branch .LBB0_1487

; DEV unsigned cvt_pk_bf16(float lo, float hi) { unsigned r; asm volatile("v_cvt_pk_bf16_f32 %0, %1, %2" : "=v"(r) : "v"(lo), "v"(hi)); return r; }
;     DEV void operator()(const Acc& acc, const Unit& u, int wr, int wc, int fr, int fq, LAS unsigned char* misc) const {
;     ...
;                     for (int n = 0; n < 2; ++n) { const int c = bj * 128 + wc * 32 + n * 16 + 4 * fq; const f32x4 a = acc[ai][bj][m][n];
;                         if (isq) { sq += (a[0] * a[0] + a[1] * a[1]) + (a[2] * a[2] + a[3] * a[3]);
;                             if (row < TX) { const f32x4 g = *(const f32x4*)(gq + c); u32x2 w; w.x = cvt_pk_bf16(a[0] * g[0], a[1] * g[1]); w.y = cvt_pk_bf16(a[2] * g[2], a[3] * g[3]); *(u32x2*)(aqn + (size_t)row * 256 + c) = w; } }
;                         else if (bj == 0) { sq += (a[0] * a[0] + a[1] * a[1]) + (a[2] * a[2] + a[3] * a[3]);
;                             const f32x4 g = *(const f32x4*)(gk + c); u32x2 w; w.x = cvt_pk_bf16(a[0] * g[0], a[1] * g[1]); w.y = cvt_pk_bf16(a[2] * g[2], a[3] * g[3]); *(u32x2*)(ckvn + (size_t)row * 128 + c) = w; }
.LBB0_1480:
	s_and_saveexec_b64 s[4:5], s[8:9]
	s_cbranch_execz .LBB0_1482
	v_ashrrev_i32_e32 v141, 31, v140
	v_lshl_add_u64 v[158:159], v[140:141], 2, s[54:55]
	v_mov_b32_e32 v158, v198
	v_mov_b32_e32 v159, v199
	v_mov_b32_e32 v160, v200
	v_mov_b32_e32 v161, v201
	v_mul_f32_e32 v143, v122, v158
	v_mul_f32_e32 v157, v123, v159
	v_cvt_pk_bf16_f32 v158, v143, v157
	v_mul_f32_e32 v143, v124, v160
	v_mul_f32_e32 v157, v125, v161
	v_lshl_add_u64 v[160:161], s[74:75], 0, v[144:145]
	v_lshl_add_u64 v[160:161], v[140:141], 1, v[160:161]
	v_cvt_pk_bf16_f32 v159, v143, v157
	global_store_dwordx2 v[160:161], v[158:159], off

; DEV unsigned cvt_pk_bf16(float lo, float hi) { unsigned r; asm volatile("v_cvt_pk_bf16_f32 %0, %1, %2" : "=v"(r) : "v"(lo), "v"(hi)); return r; }
;     DEV void operator()(const Acc& acc, const Unit& u, int wr, int wc, int fr, int fq, LAS unsigned char* misc) const {
;     ...
;                     for (int n = 0; n < 2; ++n) { const int c = bj * 128 + wc * 32 + n * 16 + 4 * fq; const f32x4 a = acc[ai][bj][m][n];
;                         if (isq) { sq += (a[0] * a[0] + a[1] * a[1]) + (a[2] * a[2] + a[3] * a[3]);
;                             if (row < TX) { const f32x4 g = *(const f32x4*)(gq + c); u32x2 w; w.x = cvt_pk_bf16(a[0] * g[0], a[1] * g[1]); w.y = cvt_pk_bf16(a[2] * g[2], a[3] * g[3]); *(u32x2*)(aqn + (size_t)row * 256 + c) = w; } }
;                         else if (bj == 0) { sq += (a[0] * a[0] + a[1] * a[1]) + (a[2] * a[2] + a[3] * a[3]);
;                             const f32x4 g = *(const f32x4*)(gk + c); u32x2 w; w.x = cvt_pk_bf16(a[0] * g[0], a[1] * g[1]); w.y = cvt_pk_bf16(a[2] * g[2], a[3] * g[3]); *(u32x2*)(ckvn + (size_t)row * 128 + c) = w; }
.LBB0_1483:
.LBB0_1484:
	s_and_saveexec_b64 s[6:7], s[8:9]
	s_cbranch_execz .LBB0_1486
	v_ashrrev_i32_e32 v141, 31, v140
	v_lshl_add_u64 v[148:149], v[140:141], 2, s[54:55]
	v_mov_b32_e32 v158, v202
	v_mov_b32_e32 v159, v203
	v_mov_b32_e32 v160, v204
	v_mov_b32_e32 v161, v205
	v_mul_f32_e32 v143, v126, v158
	v_mul_f32_e32 v148, v127, v159
	v_lshl_add_u64 v[158:159], s[74:75], 0, v[144:145]
	v_mul_f32_e32 v149, v129, v161
	v_lshl_add_u64 v[158:159], v[140:141], 1, v[158:159]
	v_cvt_pk_bf16_f32 v148, v143, v148
	v_mul_f32_e32 v143, v128, v160
	v_cvt_pk_bf16_f32 v149, v143, v149
	global_store_dwordx2 v[158:159], v[148:149], off offset:32

; DEV unsigned cvt_pk_bf16(float lo, float hi) { unsigned r; asm volatile("v_cvt_pk_bf16_f32 %0, %1, %2" : "=v"(r) : "v"(lo), "v"(hi)); return r; }
;     DEV void operator()(const Acc& acc, const Unit& u, int wr, int wc, int fr, int fq, LAS unsigned char* misc) const {
;     ...
;                     for (int n = 0; n < 2; ++n) { const int c = bj * 128 + wc * 32 + n * 16 + 4 * fq; const f32x4 a = acc[ai][bj][m][n];
;                         if (isq) { sq += (a[0] * a[0] + a[1] * a[1]) + (a[2] * a[2] + a[3] * a[3]);
;                             if (row < TX) { const f32x4 g = *(const f32x4*)(gq + c); u32x2 w; w.x = cvt_pk_bf16(a[0] * g[0], a[1] * g[1]); w.y = cvt_pk_bf16(a[2] * g[2], a[3] * g[3]); *(u32x2*)(aqn + (size_t)row * 256 + c) = w; } }
;                         else if (bj == 0) { sq += (a[0] * a[0] + a[1] * a[1]) + (a[2] * a[2] + a[3] * a[3]);
;                             const f32x4 g = *(const f32x4*)(gk + c); u32x2 w; w.x = cvt_pk_bf16(a[0] * g[0], a[1] * g[1]); w.y = cvt_pk_bf16(a[2] * g[2], a[3] * g[3]); *(u32x2*)(ckvn + (size_t)row * 128 + c) = w; }
.LBB0_1492:
	v_mul_f32_e32 v127, v127, v127
	v_mul_f32_e32 v123, v123, v123
	v_fmac_f32_e32 v127, v126, v126
	v_mul_f32_e32 v126, v129, v129
	v_fmac_f32_e32 v123, v122, v122
	v_mul_f32_e32 v122, v125, v125
	v_fmac_f32_e32 v126, v128, v128
	v_fmac_f32_e32 v122, v124, v124
	v_add_f32_e32 v126, v127, v126
	v_add_f32_e32 v122, v123, v122
	s_andn2_b64 vcc, exec, s[10:11]
	v_add_f32_e32 v122, v122, v126
	s_cbranch_vccnz .LBB0_1496
	s_and_saveexec_b64 s[10:11], s[8:9]
	s_cbranch_execz .LBB0_1495
	v_ashrrev_i32_e32 v141, 31, v140
	v_lshl_add_u64 v[124:125], v[140:141], 2, s[54:55]
	v_mov_b32_e32 v124, v206
	v_mov_b32_e32 v125, v207
	v_mov_b32_e32 v126, v208
	v_mov_b32_e32 v127, v209
	v_mul_f32_e32 v123, v118, v124
	v_mul_f32_e32 v124, v119, v125
	v_cvt_pk_bf16_f32 v124, v123, v124
	v_mul_f32_e32 v123, v120, v126
	v_mul_f32_e32 v125, v121, v127
	v_lshl_add_u64 v[126:127], s[74:75], 0, v[144:145]
	v_lshl_add_u64 v[126:127], v[140:141], 1, v[126:127]
	v_cvt_pk_bf16_f32 v125, v123, v125
	global_store_dwordx2 v[126:127], v[124:125], off offset:256

; DEV unsigned cvt_pk_bf16(float lo, float hi) { unsigned r; asm volatile("v_cvt_pk_bf16_f32 %0, %1, %2" : "=v"(r) : "v"(lo), "v"(hi)); return r; }
;     DEV void operator()(const Acc& acc, const Unit& u, int wr, int wc, int fr, int fq, LAS unsigned char* misc) const {
;     ...
;                     for (int n = 0; n < 2; ++n) { const int c = bj * 128 + wc * 32 + n * 16 + 4 * fq; const f32x4 a = acc[ai][bj][m][n];
;                         if (isq) { sq += (a[0] * a[0] + a[1] * a[1]) + (a[2] * a[2] + a[3] * a[3]);
;                             if (row < TX) { const f32x4 g = *(const f32x4*)(gq + c); u32x2 w; w.x = cvt_pk_bf16(a[0] * g[0], a[1] * g[1]); w.y = cvt_pk_bf16(a[2] * g[2], a[3] * g[3]); *(u32x2*)(aqn + (size_t)row * 256 + c) = w; } }
;                         else if (bj == 0) { sq += (a[0] * a[0] + a[1] * a[1]) + (a[2] * a[2] + a[3] * a[3]);
;                             const f32x4 g = *(const f32x4*)(gk + c); u32x2 w; w.x = cvt_pk_bf16(a[0] * g[0], a[1] * g[1]); w.y = cvt_pk_bf16(a[2] * g[2], a[3] * g[3]); *(u32x2*)(ckvn + (size_t)row * 128 + c) = w; }
.LBB0_1500:
.LBB0_1501:
	s_and_saveexec_b64 s[10:11], s[8:9]
	s_cbranch_execz .LBB0_1503
	v_ashrrev_i32_e32 v141, 31, v140
	v_lshl_add_u64 v[118:119], v[140:141], 2, s[54:55]
	v_mov_b32_e32 v118, v210
	v_mov_b32_e32 v119, v211
	v_mov_b32_e32 v120, v212
	v_mov_b32_e32 v121, v213
	v_lshl_add_u64 v[124:125], s[74:75], 0, v[144:145]
	v_mul_f32_e32 v118, v114, v118
	v_mul_f32_e32 v119, v115, v119
	v_mul_f32_e32 v120, v116, v120
	v_mul_f32_e32 v121, v117, v121
	v_cvt_pk_bf16_f32 v118, v118, v119
	v_cvt_pk_bf16_f32 v119, v120, v121
	v_lshl_add_u64 v[120:121], v[140:141], 1, v[124:125]
	global_store_dwordx2 v[120:121], v[118:119], off offset:288

; DEV unsigned cvt_pk_bf16(float lo, float hi) { unsigned r; asm volatile("v_cvt_pk_bf16_f32 %0, %1, %2" : "=v"(r) : "v"(lo), "v"(hi)); return r; }
;     DEV void operator()(const Acc& acc, const Unit& u, int wr, int wc, int fr, int fq, LAS unsigned char* misc) const {
;     ...
;             for (int m = 0; m < 4; ++m) { const int rl = ai * 128 + wr * 64 + m * 16 + fr, row = rt + rl; float sq = 0.f;
; #pragma unroll
;                 for (int bj = 0; bj < 2; ++bj)
; #pragma unroll
;                     for (int n = 0; n < 2; ++n) { const int c = bj * 128 + wc * 32 + n * 16 + 4 * fq; const f32x4 a = acc[ai][bj][m][n];
;                         if (isq) { sq += (a[0] * a[0] + a[1] * a[1]) + (a[2] * a[2] + a[3] * a[3]);
;                             if (row < TX) { const f32x4 g = *(const f32x4*)(gq + c); u32x2 w; w.x = cvt_pk_bf16(a[0] * g[0], a[1] * g[1]); w.y = cvt_pk_bf16(a[2] * g[2], a[3] * g[3]); *(u32x2*)(aqn + (size_t)row * 256 + c) = w; } }
;                         else if (bj == 0) { sq += (a[0] * a[0] + a[1] * a[1]) + (a[2] * a[2] + a[3] * a[3]);
;                             const f32x4 g = *(const f32x4*)(gk + c); u32x2 w; w.x = cvt_pk_bf16(a[0] * g[0], a[1] * g[1]); w.y = cvt_pk_bf16(a[2] * g[2], a[3] * g[3]); *(u32x2*)(ckvn + (size_t)row * 128 + c) = w; }
;                         else if (wc == 0) { *(f32x4*)(kpe + (size_t)row * 32 + n * 16 + 4 * fq) = a; } }
.LBB0_1506:
	s_or_b64 exec, exec, s[10:11]
	v_add_u32_e32 v122, 16, v156
	v_add_u32_e32 v116, s19, v122
	v_ashrrev_i32_e32 v117, 31, v116
	s_waitcnt lgkmcnt(0)
	v_lshlrev_b64 v[114:115], 8, v[116:117]
	v_cmp_gt_i32_e64 s[10:11], s97, v116
	s_and_b64 vcc, exec, s[4:5]
	v_lshl_add_u64 v[118:119], s[68:69], 0, v[114:115]
	s_cbranch_vccnz .LBB0_1514
	v_ashrrev_i32_e32 v141, 31, v140
	v_lshl_add_u64 v[114:115], v[140:141], 2, s[50:51]
	v_mov_b32_e32 v124, v190
	v_mov_b32_e32 v125, v191
	v_mov_b32_e32 v126, v192
	v_mov_b32_e32 v127, v193
	v_lshl_add_u64 v[114:115], v[140:141], 1, v[118:119]
	v_mul_f32_e32 v123, v106, v124
	v_mul_f32_e32 v124, v107, v125
	v_mul_f32_e32 v125, v108, v126
	v_mul_f32_e32 v126, v109, v127
	v_cvt_pk_bf16_f32 v124, v123, v124
	v_cvt_pk_bf16_f32 v125, v125, v126
	global_store_dwordx2 v[114:115], v[124:125], off
	v_lshlrev_b64 v[114:115], 9, v[116:117]
	s_cbranch_execz .LBB0_1515
	s_and_b64 vcc, exec, s[4:5]
	s_cbranch_vccnz .LBB0_1518
.LBB0_1509:
	v_ashrrev_i32_e32 v141, 31, v140
	v_lshl_add_u64 v[124:125], v[140:141], 2, s[50:51]
	v_mov_b32_e32 v124, v194
	v_mov_b32_e32 v125, v195
	v_mov_b32_e32 v126, v196
	v_mov_b32_e32 v127, v197
	v_lshl_add_u64 v[118:119], v[140:141], 1, v[118:119]
	v_mul_f32_e32 v123, v110, v124
	v_mul_f32_e32 v124, v111, v125
	v_mul_f32_e32 v125, v112, v126
	v_mul_f32_e32 v126, v113, v127
	v_cvt_pk_bf16_f32 v124, v123, v124
	v_cvt_pk_bf16_f32 v125, v125, v126
	global_store_dwordx2 v[118:119], v[124:125], off offset:32
	s_cbranch_execz .LBB0_1519
	s_and_b64 vcc, exec, s[4:5]
	v_lshlrev_b64 v[116:117], 7, v[116:117]
	s_cbranch_vccnz .LBB0_1522

; DEV unsigned cvt_pk_bf16(float lo, float hi) { unsigned r; asm volatile("v_cvt_pk_bf16_f32 %0, %1, %2" : "=v"(r) : "v"(lo), "v"(hi)); return r; }
;     DEV void operator()(const Acc& acc, const Unit& u, int wr, int wc, int fr, int fq, LAS unsigned char* misc) const {
;     ...
;                     for (int n = 0; n < 2; ++n) { const int c = bj * 128 + wc * 32 + n * 16 + 4 * fq; const f32x4 a = acc[ai][bj][m][n];
;                         if (isq) { sq += (a[0] * a[0] + a[1] * a[1]) + (a[2] * a[2] + a[3] * a[3]);
;                             if (row < TX) { const f32x4 g = *(const f32x4*)(gq + c); u32x2 w; w.x = cvt_pk_bf16(a[0] * g[0], a[1] * g[1]); w.y = cvt_pk_bf16(a[2] * g[2], a[3] * g[3]); *(u32x2*)(aqn + (size_t)row * 256 + c) = w; } }
;                         else if (bj == 0) { sq += (a[0] * a[0] + a[1] * a[1]) + (a[2] * a[2] + a[3] * a[3]);
;                             const f32x4 g = *(const f32x4*)(gk + c); u32x2 w; w.x = cvt_pk_bf16(a[0] * g[0], a[1] * g[1]); w.y = cvt_pk_bf16(a[2] * g[2], a[3] * g[3]); *(u32x2*)(ckvn + (size_t)row * 128 + c) = w; }
.LBB0_1515:
	s_and_saveexec_b64 s[46:47], s[10:11]
	s_cbranch_execz .LBB0_1517
	v_ashrrev_i32_e32 v141, 31, v140
	v_lshl_add_u64 v[124:125], v[140:141], 2, s[54:55]
	v_mov_b32_e32 v124, v198
	v_mov_b32_e32 v125, v199
	v_mov_b32_e32 v126, v200
	v_mov_b32_e32 v127, v201
	v_mul_f32_e32 v123, v106, v124
	v_mul_f32_e32 v124, v107, v125
	v_cvt_pk_bf16_f32 v124, v123, v124
	v_mul_f32_e32 v123, v108, v126
	v_mul_f32_e32 v125, v109, v127
	v_lshl_add_u64 v[126:127], s[74:75], 0, v[114:115]
	v_lshl_add_u64 v[126:127], v[140:141], 1, v[126:127]
	v_cvt_pk_bf16_f32 v125, v123, v125
	global_store_dwordx2 v[126:127], v[124:125], off

; DEV unsigned cvt_pk_bf16(float lo, float hi) { unsigned r; asm volatile("v_cvt_pk_bf16_f32 %0, %1, %2" : "=v"(r) : "v"(lo), "v"(hi)); return r; }
;     DEV void operator()(const Acc& acc, const Unit& u, int wr, int wc, int fr, int fq, LAS unsigned char* misc) const {
;     ...
;                     for (int n = 0; n < 2; ++n) { const int c = bj * 128 + wc * 32 + n * 16 + 4 * fq; const f32x4 a = acc[ai][bj][m][n];
;                         if (isq) { sq += (a[0] * a[0] + a[1] * a[1]) + (a[2] * a[2] + a[3] * a[3]);
;                             if (row < TX) { const f32x4 g = *(const f32x4*)(gq + c); u32x2 w; w.x = cvt_pk_bf16(a[0] * g[0], a[1] * g[1]); w.y = cvt_pk_bf16(a[2] * g[2], a[3] * g[3]); *(u32x2*)(aqn + (size_t)row * 256 + c) = w; } }
;                         else if (bj == 0) { sq += (a[0] * a[0] + a[1] * a[1]) + (a[2] * a[2] + a[3] * a[3]);
;                             const f32x4 g = *(const f32x4*)(gk + c); u32x2 w; w.x = cvt_pk_bf16(a[0] * g[0], a[1] * g[1]); w.y = cvt_pk_bf16(a[2] * g[2], a[3] * g[3]); *(u32x2*)(ckvn + (size_t)row * 128 + c) = w; }
.LBB0_1518:
.LBB0_1519:
	s_and_saveexec_b64 s[46:47], s[10:11]
	s_cbranch_execz .LBB0_1521
	v_ashrrev_i32_e32 v141, 31, v140
	v_lshl_add_u64 v[118:119], v[140:141], 2, s[54:55]
	v_mov_b32_e32 v124, v202
	v_mov_b32_e32 v125, v203
	v_mov_b32_e32 v126, v204
	v_mov_b32_e32 v127, v205
	v_mul_f32_e32 v118, v110, v124
	v_mul_f32_e32 v119, v111, v125
	v_lshl_add_u64 v[124:125], s[74:75], 0, v[114:115]
	v_cvt_pk_bf16_f32 v118, v118, v119
	v_mul_f32_e32 v119, v112, v126
	v_lshl_add_u64 v[124:125], v[140:141], 1, v[124:125]
	v_mul_f32_e32 v123, v113, v127
	v_cvt_pk_bf16_f32 v119, v119, v123
	global_store_dwordx2 v[124:125], v[118:119], off offset:32

; DEV unsigned cvt_pk_bf16(float lo, float hi) { unsigned r; asm volatile("v_cvt_pk_bf16_f32 %0, %1, %2" : "=v"(r) : "v"(lo), "v"(hi)); return r; }
;     DEV void operator()(const Acc& acc, const Unit& u, int wr, int wc, int fr, int fq, LAS unsigned char* misc) const {
;     ...
;                     for (int n = 0; n < 2; ++n) { const int c = bj * 128 + wc * 32 + n * 16 + 4 * fq; const f32x4 a = acc[ai][bj][m][n];
;                         if (isq) { sq += (a[0] * a[0] + a[1] * a[1]) + (a[2] * a[2] + a[3] * a[3]);
;                             if (row < TX) { const f32x4 g = *(const f32x4*)(gq + c); u32x2 w; w.x = cvt_pk_bf16(a[0] * g[0], a[1] * g[1]); w.y = cvt_pk_bf16(a[2] * g[2], a[3] * g[3]); *(u32x2*)(aqn + (size_t)row * 256 + c) = w; } }
;                         else if (bj == 0) { sq += (a[0] * a[0] + a[1] * a[1]) + (a[2] * a[2] + a[3] * a[3]);
;                             const f32x4 g = *(const f32x4*)(gk + c); u32x2 w; w.x = cvt_pk_bf16(a[0] * g[0], a[1] * g[1]); w.y = cvt_pk_bf16(a[2] * g[2], a[3] * g[3]); *(u32x2*)(ckvn + (size_t)row * 128 + c) = w; }
.LBB0_1523:
	v_mul_f32_e32 v111, v111, v111
	v_mul_f32_e32 v107, v107, v107
	v_fmac_f32_e32 v111, v110, v110
	v_mul_f32_e32 v110, v113, v113
	v_fmac_f32_e32 v107, v106, v106
	v_mul_f32_e32 v106, v109, v109
	v_fmac_f32_e32 v110, v112, v112
	v_fmac_f32_e32 v106, v108, v108
	v_add_f32_e32 v110, v111, v110
	v_add_f32_e32 v106, v107, v106
	s_andn2_b64 vcc, exec, s[46:47]
	v_add_f32_e32 v106, v106, v110
	s_cbranch_vccnz .LBB0_1527
	s_and_saveexec_b64 s[46:47], s[10:11]
	s_cbranch_execz .LBB0_1526
	v_ashrrev_i32_e32 v141, 31, v140
	v_lshl_add_u64 v[108:109], v[140:141], 2, s[54:55]
	v_mov_b32_e32 v108, v206
	v_mov_b32_e32 v109, v207
	v_mov_b32_e32 v110, v208
	v_mov_b32_e32 v111, v209
	v_mul_f32_e32 v107, v102, v108
	v_mul_f32_e32 v108, v103, v109
	v_cvt_pk_bf16_f32 v108, v107, v108
	v_mul_f32_e32 v107, v104, v110
	v_mul_f32_e32 v109, v105, v111
	v_lshl_add_u64 v[110:111], s[74:75], 0, v[114:115]
	v_lshl_add_u64 v[110:111], v[140:141], 1, v[110:111]
	v_cvt_pk_bf16_f32 v109, v107, v109
	global_store_dwordx2 v[110:111], v[108:109], off offset:256

; DEV unsigned cvt_pk_bf16(float lo, float hi) { unsigned r; asm volatile("v_cvt_pk_bf16_f32 %0, %1, %2" : "=v"(r) : "v"(lo), "v"(hi)); return r; }
;     DEV void operator()(const Acc& acc, const Unit& u, int wr, int wc, int fr, int fq, LAS unsigned char* misc) const {
;     ...
;                     for (int n = 0; n < 2; ++n) { const int c = bj * 128 + wc * 32 + n * 16 + 4 * fq; const f32x4 a = acc[ai][bj][m][n];
;                         if (isq) { sq += (a[0] * a[0] + a[1] * a[1]) + (a[2] * a[2] + a[3] * a[3]);
;                             if (row < TX) { const f32x4 g = *(const f32x4*)(gq + c); u32x2 w; w.x = cvt_pk_bf16(a[0] * g[0], a[1] * g[1]); w.y = cvt_pk_bf16(a[2] * g[2], a[3] * g[3]); *(u32x2*)(aqn + (size_t)row * 256 + c) = w; } }
;                         else if (bj == 0) { sq += (a[0] * a[0] + a[1] * a[1]) + (a[2] * a[2] + a[3] * a[3]);
;                             const f32x4 g = *(const f32x4*)(gk + c); u32x2 w; w.x = cvt_pk_bf16(a[0] * g[0], a[1] * g[1]); w.y = cvt_pk_bf16(a[2] * g[2], a[3] * g[3]); *(u32x2*)(ckvn + (size_t)row * 128 + c) = w; }
.LBB0_1531:
.LBB0_1532:
	s_and_saveexec_b64 s[46:47], s[10:11]
	s_cbranch_execz .LBB0_1534
	v_ashrrev_i32_e32 v141, 31, v140
	v_lshl_add_u64 v[102:103], v[140:141], 2, s[54:55]
	v_mov_b32_e32 v102, v210
	v_mov_b32_e32 v103, v211
	v_mov_b32_e32 v104, v212
	v_mov_b32_e32 v105, v213
	v_lshl_add_u64 v[108:109], s[74:75], 0, v[114:115]
	v_mul_f32_e32 v102, v98, v102
	v_mul_f32_e32 v103, v99, v103
	v_mul_f32_e32 v104, v100, v104
	v_mul_f32_e32 v105, v101, v105
	v_cvt_pk_bf16_f32 v102, v102, v103
	v_cvt_pk_bf16_f32 v103, v104, v105
	v_lshl_add_u64 v[104:105], v[140:141], 1, v[108:109]
	global_store_dwordx2 v[104:105], v[102:103], off offset:288

; DEV unsigned cvt_pk_bf16(float lo, float hi) { unsigned r; asm volatile("v_cvt_pk_bf16_f32 %0, %1, %2" : "=v"(r) : "v"(lo), "v"(hi)); return r; }
;     DEV void operator()(const Acc& acc, const Unit& u, int wr, int wc, int fr, int fq, LAS unsigned char* misc) const {
;     ...
;             for (int m = 0; m < 4; ++m) { const int rl = ai * 128 + wr * 64 + m * 16 + fr, row = rt + rl; float sq = 0.f;
; #pragma unroll
;                 for (int bj = 0; bj < 2; ++bj)
; #pragma unroll
;                     for (int n = 0; n < 2; ++n) { const int c = bj * 128 + wc * 32 + n * 16 + 4 * fq; const f32x4 a = acc[ai][bj][m][n];
;                         if (isq) { sq += (a[0] * a[0] + a[1] * a[1]) + (a[2] * a[2] + a[3] * a[3]);
;                             if (row < TX) { const f32x4 g = *(const f32x4*)(gq + c); u32x2 w; w.x = cvt_pk_bf16(a[0] * g[0], a[1] * g[1]); w.y = cvt_pk_bf16(a[2] * g[2], a[3] * g[3]); *(u32x2*)(aqn + (size_t)row * 256 + c) = w; } }
;                         else if (bj == 0) { sq += (a[0] * a[0] + a[1] * a[1]) + (a[2] * a[2] + a[3] * a[3]);
;                             const f32x4 g = *(const f32x4*)(gk + c); u32x2 w; w.x = cvt_pk_bf16(a[0] * g[0], a[1] * g[1]); w.y = cvt_pk_bf16(a[2] * g[2], a[3] * g[3]); *(u32x2*)(ckvn + (size_t)row * 128 + c) = w; }
;                         else if (wc == 0) { *(f32x4*)(kpe + (size_t)row * 32 + n * 16 + 4 * fq) = a; } }
.LBB0_1537:
	s_or_b64 exec, exec, s[10:11]
	v_add_u32_e32 v104, 32, v156
	v_add_u32_e32 v100, s19, v104
	v_ashrrev_i32_e32 v101, 31, v100
	s_waitcnt lgkmcnt(0)
	v_lshlrev_b64 v[98:99], 8, v[100:101]
	v_cmp_gt_i32_e64 s[10:11], s97, v100
	s_and_b64 vcc, exec, s[4:5]
	v_lshl_add_u64 v[102:103], s[68:69], 0, v[98:99]
	s_cbranch_vccnz .LBB0_1545
	v_ashrrev_i32_e32 v141, 31, v140
	v_lshl_add_u64 v[98:99], v[140:141], 2, s[50:51]
	v_mov_b32_e32 v106, v190
	v_mov_b32_e32 v107, v191
	v_mov_b32_e32 v108, v192
	v_mov_b32_e32 v109, v193
	v_lshl_add_u64 v[98:99], v[140:141], 1, v[102:103]
	v_mul_f32_e32 v105, v88, v106
	v_mul_f32_e32 v106, v89, v107
	v_mul_f32_e32 v107, v90, v108
	v_mul_f32_e32 v108, v91, v109
	v_cvt_pk_bf16_f32 v106, v105, v106
	v_cvt_pk_bf16_f32 v107, v107, v108
	global_store_dwordx2 v[98:99], v[106:107], off
	v_lshlrev_b64 v[98:99], 9, v[100:101]
	s_cbranch_execz .LBB0_1546
	s_and_b64 vcc, exec, s[4:5]
	s_cbranch_vccnz .LBB0_1549
.LBB0_1540:
	v_ashrrev_i32_e32 v141, 31, v140
	v_lshl_add_u64 v[106:107], v[140:141], 2, s[50:51]
	v_mov_b32_e32 v106, v194
	v_mov_b32_e32 v107, v195
	v_mov_b32_e32 v108, v196
	v_mov_b32_e32 v109, v197
	v_lshl_add_u64 v[102:103], v[140:141], 1, v[102:103]
	v_mul_f32_e32 v105, v92, v106
	v_mul_f32_e32 v106, v93, v107
	v_mul_f32_e32 v107, v94, v108
	v_mul_f32_e32 v108, v95, v109
	v_cvt_pk_bf16_f32 v106, v105, v106
	v_cvt_pk_bf16_f32 v107, v107, v108
	global_store_dwordx2 v[102:103], v[106:107], off offset:32
	s_cbranch_execz .LBB0_1550
	s_and_b64 vcc, exec, s[4:5]
	v_lshlrev_b64 v[100:101], 7, v[100:101]
	s_cbranch_vccnz .LBB0_1553

; DEV unsigned cvt_pk_bf16(float lo, float hi) { unsigned r; asm volatile("v_cvt_pk_bf16_f32 %0, %1, %2" : "=v"(r) : "v"(lo), "v"(hi)); return r; }
;     DEV void operator()(const Acc& acc, const Unit& u, int wr, int wc, int fr, int fq, LAS unsigned char* misc) const {
;     ...
;                     for (int n = 0; n < 2; ++n) { const int c = bj * 128 + wc * 32 + n * 16 + 4 * fq; const f32x4 a = acc[ai][bj][m][n];
;                         if (isq) { sq += (a[0] * a[0] + a[1] * a[1]) + (a[2] * a[2] + a[3] * a[3]);
;                             if (row < TX) { const f32x4 g = *(const f32x4*)(gq + c); u32x2 w; w.x = cvt_pk_bf16(a[0] * g[0], a[1] * g[1]); w.y = cvt_pk_bf16(a[2] * g[2], a[3] * g[3]); *(u32x2*)(aqn + (size_t)row * 256 + c) = w; } }
;                         else if (bj == 0) { sq += (a[0] * a[0] + a[1] * a[1]) + (a[2] * a[2] + a[3] * a[3]);
;                             const f32x4 g = *(const f32x4*)(gk + c); u32x2 w; w.x = cvt_pk_bf16(a[0] * g[0], a[1] * g[1]); w.y = cvt_pk_bf16(a[2] * g[2], a[3] * g[3]); *(u32x2*)(ckvn + (size_t)row * 128 + c) = w; }
.LBB0_1546:
	s_and_saveexec_b64 s[46:47], s[10:11]
	s_cbranch_execz .LBB0_1548
	v_ashrrev_i32_e32 v141, 31, v140
	v_lshl_add_u64 v[106:107], v[140:141], 2, s[54:55]
	v_mov_b32_e32 v106, v198
	v_mov_b32_e32 v107, v199
	v_mov_b32_e32 v108, v200
	v_mov_b32_e32 v109, v201
	v_mul_f32_e32 v105, v88, v106
	v_mul_f32_e32 v106, v89, v107
	v_cvt_pk_bf16_f32 v106, v105, v106
	v_mul_f32_e32 v105, v90, v108
	v_mul_f32_e32 v107, v91, v109
	v_lshl_add_u64 v[108:109], s[74:75], 0, v[98:99]
	v_lshl_add_u64 v[108:109], v[140:141], 1, v[108:109]
	v_cvt_pk_bf16_f32 v107, v105, v107
	global_store_dwordx2 v[108:109], v[106:107], off

; DEV unsigned cvt_pk_bf16(float lo, float hi) { unsigned r; asm volatile("v_cvt_pk_bf16_f32 %0, %1, %2" : "=v"(r) : "v"(lo), "v"(hi)); return r; }
;     DEV void operator()(const Acc& acc, const Unit& u, int wr, int wc, int fr, int fq, LAS unsigned char* misc) const {
;     ...
;                     for (int n = 0; n < 2; ++n) { const int c = bj * 128 + wc * 32 + n * 16 + 4 * fq; const f32x4 a = acc[ai][bj][m][n];
;                         if (isq) { sq += (a[0] * a[0] + a[1] * a[1]) + (a[2] * a[2] + a[3] * a[3]);
;                             if (row < TX) { const f32x4 g = *(const f32x4*)(gq + c); u32x2 w; w.x = cvt_pk_bf16(a[0] * g[0], a[1] * g[1]); w.y = cvt_pk_bf16(a[2] * g[2], a[3] * g[3]); *(u32x2*)(aqn + (size_t)row * 256 + c) = w; } }
;                         else if (bj == 0) { sq += (a[0] * a[0] + a[1] * a[1]) + (a[2] * a[2] + a[3] * a[3]);
;                             const f32x4 g = *(const f32x4*)(gk + c); u32x2 w; w.x = cvt_pk_bf16(a[0] * g[0], a[1] * g[1]); w.y = cvt_pk_bf16(a[2] * g[2], a[3] * g[3]); *(u32x2*)(ckvn + (size_t)row * 128 + c) = w; }
.LBB0_1549:
.LBB0_1550:
	s_and_saveexec_b64 s[46:47], s[10:11]
	s_cbranch_execz .LBB0_1552
	v_ashrrev_i32_e32 v141, 31, v140
	v_lshl_add_u64 v[102:103], v[140:141], 2, s[54:55]
	v_mov_b32_e32 v106, v202
	v_mov_b32_e32 v107, v203
	v_mov_b32_e32 v108, v204
	v_mov_b32_e32 v109, v205
	v_mul_f32_e32 v102, v92, v106
	v_mul_f32_e32 v103, v93, v107
	v_lshl_add_u64 v[106:107], s[74:75], 0, v[98:99]
	v_cvt_pk_bf16_f32 v102, v102, v103
	v_mul_f32_e32 v103, v94, v108
	v_lshl_add_u64 v[106:107], v[140:141], 1, v[106:107]
	v_mul_f32_e32 v105, v95, v109
	v_cvt_pk_bf16_f32 v103, v103, v105
	global_store_dwordx2 v[106:107], v[102:103], off offset:32

; DEV unsigned cvt_pk_bf16(float lo, float hi) { unsigned r; asm volatile("v_cvt_pk_bf16_f32 %0, %1, %2" : "=v"(r) : "v"(lo), "v"(hi)); return r; }
;     DEV void operator()(const Acc& acc, const Unit& u, int wr, int wc, int fr, int fq, LAS unsigned char* misc) const {
;     ...
;                     for (int n = 0; n < 2; ++n) { const int c = bj * 128 + wc * 32 + n * 16 + 4 * fq; const f32x4 a = acc[ai][bj][m][n];
;                         if (isq) { sq += (a[0] * a[0] + a[1] * a[1]) + (a[2] * a[2] + a[3] * a[3]);
;                             if (row < TX) { const f32x4 g = *(const f32x4*)(gq + c); u32x2 w; w.x = cvt_pk_bf16(a[0] * g[0], a[1] * g[1]); w.y = cvt_pk_bf16(a[2] * g[2], a[3] * g[3]); *(u32x2*)(aqn + (size_t)row * 256 + c) = w; } }
;                         else if (bj == 0) { sq += (a[0] * a[0] + a[1] * a[1]) + (a[2] * a[2] + a[3] * a[3]);
;                             const f32x4 g = *(const f32x4*)(gk + c); u32x2 w; w.x = cvt_pk_bf16(a[0] * g[0], a[1] * g[1]); w.y = cvt_pk_bf16(a[2] * g[2], a[3] * g[3]); *(u32x2*)(ckvn + (size_t)row * 128 + c) = w; }
.LBB0_1554:
	v_mul_f32_e32 v93, v93, v93
	v_mul_f32_e32 v89, v89, v89
	v_fmac_f32_e32 v93, v92, v92
	v_mul_f32_e32 v92, v95, v95
	v_fmac_f32_e32 v89, v88, v88
	v_mul_f32_e32 v88, v91, v91
	v_fmac_f32_e32 v92, v94, v94
	v_fmac_f32_e32 v88, v90, v90
	v_add_f32_e32 v92, v93, v92
	v_add_f32_e32 v88, v89, v88
	s_andn2_b64 vcc, exec, s[46:47]
	v_add_f32_e32 v88, v88, v92
	s_cbranch_vccnz .LBB0_1558
	s_and_saveexec_b64 s[46:47], s[10:11]
	s_cbranch_execz .LBB0_1557
	v_ashrrev_i32_e32 v141, 31, v140
	v_lshl_add_u64 v[90:91], v[140:141], 2, s[54:55]
	v_mov_b32_e32 v90, v206
	v_mov_b32_e32 v91, v207
	v_mov_b32_e32 v92, v208
	v_mov_b32_e32 v93, v209
	v_mul_f32_e32 v89, v84, v90
	v_mul_f32_e32 v90, v85, v91
	v_cvt_pk_bf16_f32 v90, v89, v90
	v_mul_f32_e32 v89, v86, v92
	v_mul_f32_e32 v91, v87, v93
	v_lshl_add_u64 v[92:93], s[74:75], 0, v[98:99]
	v_lshl_add_u64 v[92:93], v[140:141], 1, v[92:93]
	v_cvt_pk_bf16_f32 v91, v89, v91
	global_store_dwordx2 v[92:93], v[90:91], off offset:256

; DEV unsigned cvt_pk_bf16(float lo, float hi) { unsigned r; asm volatile("v_cvt_pk_bf16_f32 %0, %1, %2" : "=v"(r) : "v"(lo), "v"(hi)); return r; }
;     DEV void operator()(const Acc& acc, const Unit& u, int wr, int wc, int fr, int fq, LAS unsigned char* misc) const {
;     ...
;                     for (int n = 0; n < 2; ++n) { const int c = bj * 128 + wc * 32 + n * 16 + 4 * fq; const f32x4 a = acc[ai][bj][m][n];
;                         if (isq) { sq += (a[0] * a[0] + a[1] * a[1]) + (a[2] * a[2] + a[3] * a[3]);
;                             if (row < TX) { const f32x4 g = *(const f32x4*)(gq + c); u32x2 w; w.x = cvt_pk_bf16(a[0] * g[0], a[1] * g[1]); w.y = cvt_pk_bf16(a[2] * g[2], a[3] * g[3]); *(u32x2*)(aqn + (size_t)row * 256 + c) = w; } }
;                         else if (bj == 0) { sq += (a[0] * a[0] + a[1] * a[1]) + (a[2] * a[2] + a[3] * a[3]);
;                             const f32x4 g = *(const f32x4*)(gk + c); u32x2 w; w.x = cvt_pk_bf16(a[0] * g[0], a[1] * g[1]); w.y = cvt_pk_bf16(a[2] * g[2], a[3] * g[3]); *(u32x2*)(ckvn + (size_t)row * 128 + c) = w; }
;                         else if (wc == 0) { *(f32x4*)(kpe + (size_t)row * 32 + n * 16 + 4 * fq) = a; } }
.LBB0_1562:
.LBB0_1563:
	s_and_saveexec_b64 s[46:47], s[10:11]
	s_cbranch_execz .LBB0_1565
	v_ashrrev_i32_e32 v141, 31, v140
	v_lshl_add_u64 v[84:85], v[140:141], 2, s[54:55]
	v_mov_b32_e32 v84, v210
	v_mov_b32_e32 v85, v211
	v_mov_b32_e32 v86, v212
	v_mov_b32_e32 v87, v213
	v_lshl_add_u64 v[90:91], s[74:75], 0, v[98:99]
	v_mul_f32_e32 v84, v80, v84
	v_mul_f32_e32 v85, v81, v85
	v_mul_f32_e32 v86, v82, v86
	v_mul_f32_e32 v87, v83, v87
	v_cvt_pk_bf16_f32 v84, v84, v85
	v_cvt_pk_bf16_f32 v85, v86, v87
	v_lshl_add_u64 v[86:87], v[140:141], 1, v[90:91]
	global_store_dwordx2 v[86:87], v[84:85], off offset:288

; DEV unsigned cvt_pk_bf16(float lo, float hi) { unsigned r; asm volatile("v_cvt_pk_bf16_f32 %0, %1, %2" : "=v"(r) : "v"(lo), "v"(hi)); return r; }
;     DEV void operator()(const Acc& acc, const Unit& u, int wr, int wc, int fr, int fq, LAS unsigned char* misc) const {
;     ...
;             for (int m = 0; m < 4; ++m) { const int rl = ai * 128 + wr * 64 + m * 16 + fr, row = rt + rl; float sq = 0.f;
; #pragma unroll
;                 for (int bj = 0; bj < 2; ++bj)
; #pragma unroll
;                     for (int n = 0; n < 2; ++n) { const int c = bj * 128 + wc * 32 + n * 16 + 4 * fq; const f32x4 a = acc[ai][bj][m][n];
;                         if (isq) { sq += (a[0] * a[0] + a[1] * a[1]) + (a[2] * a[2] + a[3] * a[3]);
;                             if (row < TX) { const f32x4 g = *(const f32x4*)(gq + c); u32x2 w; w.x = cvt_pk_bf16(a[0] * g[0], a[1] * g[1]); w.y = cvt_pk_bf16(a[2] * g[2], a[3] * g[3]); *(u32x2*)(aqn + (size_t)row * 256 + c) = w; } }
;                         else if (bj == 0) { sq += (a[0] * a[0] + a[1] * a[1]) + (a[2] * a[2] + a[3] * a[3]);
;                             const f32x4 g = *(const f32x4*)(gk + c); u32x2 w; w.x = cvt_pk_bf16(a[0] * g[0], a[1] * g[1]); w.y = cvt_pk_bf16(a[2] * g[2], a[3] * g[3]); *(u32x2*)(ckvn + (size_t)row * 128 + c) = w; }
;                         else if (wc == 0) { *(f32x4*)(kpe + (size_t)row * 32 + n * 16 + 4 * fq) = a; } }
.LBB0_1568:
	s_or_b64 exec, exec, s[10:11]
	v_add_u32_e32 v86, 48, v156
	v_add_u32_e32 v82, s19, v86
	v_ashrrev_i32_e32 v83, 31, v82
	s_waitcnt lgkmcnt(0)
	v_lshlrev_b64 v[80:81], 8, v[82:83]
	v_cmp_gt_i32_e64 s[10:11], s97, v82
	s_and_b64 vcc, exec, s[4:5]
	v_lshl_add_u64 v[84:85], s[68:69], 0, v[80:81]
	s_cbranch_vccnz .LBB0_1576
	v_ashrrev_i32_e32 v141, 31, v140
	v_lshl_add_u64 v[80:81], v[140:141], 2, s[50:51]
	v_mov_b32_e32 v88, v190
	v_mov_b32_e32 v89, v191
	v_mov_b32_e32 v90, v192
	v_mov_b32_e32 v91, v193
	v_lshl_add_u64 v[80:81], v[140:141], 1, v[84:85]
	v_mul_f32_e32 v87, v72, v88
	v_mul_f32_e32 v88, v73, v89
	v_mul_f32_e32 v89, v74, v90
	v_mul_f32_e32 v90, v75, v91
	v_cvt_pk_bf16_f32 v88, v87, v88
	v_cvt_pk_bf16_f32 v89, v89, v90
	global_store_dwordx2 v[80:81], v[88:89], off
	v_lshlrev_b64 v[80:81], 9, v[82:83]
	s_cbranch_execz .LBB0_1577
	s_and_b64 vcc, exec, s[4:5]
	s_cbranch_vccnz .LBB0_1580
.LBB0_1571:
	v_ashrrev_i32_e32 v141, 31, v140
	v_lshl_add_u64 v[88:89], v[140:141], 2, s[50:51]
	v_mov_b32_e32 v88, v194
	v_mov_b32_e32 v89, v195
	v_mov_b32_e32 v90, v196
	v_mov_b32_e32 v91, v197
	v_lshl_add_u64 v[84:85], v[140:141], 1, v[84:85]
	v_mul_f32_e32 v87, v76, v88
	v_mul_f32_e32 v88, v77, v89
	v_mul_f32_e32 v89, v78, v90
	v_mul_f32_e32 v90, v79, v91
	v_cvt_pk_bf16_f32 v88, v87, v88
	v_cvt_pk_bf16_f32 v89, v89, v90
	global_store_dwordx2 v[84:85], v[88:89], off offset:32
	s_cbranch_execz .LBB0_1581
	s_and_b64 vcc, exec, s[4:5]
	v_lshlrev_b64 v[82:83], 7, v[82:83]
	s_cbranch_vccnz .LBB0_1584

; DEV unsigned cvt_pk_bf16(float lo, float hi) { unsigned r; asm volatile("v_cvt_pk_bf16_f32 %0, %1, %2" : "=v"(r) : "v"(lo), "v"(hi)); return r; }
;     DEV void operator()(const Acc& acc, const Unit& u, int wr, int wc, int fr, int fq, LAS unsigned char* misc) const {
;     ...
;                     for (int n = 0; n < 2; ++n) { const int c = bj * 128 + wc * 32 + n * 16 + 4 * fq; const f32x4 a = acc[ai][bj][m][n];
;                         if (isq) { sq += (a[0] * a[0] + a[1] * a[1]) + (a[2] * a[2] + a[3] * a[3]);
;                             if (row < TX) { const f32x4 g = *(const f32x4*)(gq + c); u32x2 w; w.x = cvt_pk_bf16(a[0] * g[0], a[1] * g[1]); w.y = cvt_pk_bf16(a[2] * g[2], a[3] * g[3]); *(u32x2*)(aqn + (size_t)row * 256 + c) = w; } }
.LBB0_1577:
	s_and_saveexec_b64 s[46:47], s[10:11]
	s_cbranch_execz .LBB0_1579
	v_ashrrev_i32_e32 v141, 31, v140
	v_lshl_add_u64 v[88:89], v[140:141], 2, s[54:55]
	v_mov_b32_e32 v88, v198
	v_mov_b32_e32 v89, v199
	v_mov_b32_e32 v90, v200
	v_mov_b32_e32 v91, v201
	v_mul_f32_e32 v87, v72, v88
	v_mul_f32_e32 v88, v73, v89
	v_cvt_pk_bf16_f32 v88, v87, v88
	v_mul_f32_e32 v87, v74, v90
	v_mul_f32_e32 v89, v75, v91
	v_lshl_add_u64 v[90:91], s[74:75], 0, v[80:81]
	v_lshl_add_u64 v[90:91], v[140:141], 1, v[90:91]
	v_cvt_pk_bf16_f32 v89, v87, v89
	global_store_dwordx2 v[90:91], v[88:89], off

; DEV unsigned cvt_pk_bf16(float lo, float hi) { unsigned r; asm volatile("v_cvt_pk_bf16_f32 %0, %1, %2" : "=v"(r) : "v"(lo), "v"(hi)); return r; }
;     DEV void operator()(const Acc& acc, const Unit& u, int wr, int wc, int fr, int fq, LAS unsigned char* misc) const {
;     ...
;                     for (int n = 0; n < 2; ++n) { const int c = bj * 128 + wc * 32 + n * 16 + 4 * fq; const f32x4 a = acc[ai][bj][m][n];
;                         if (isq) { sq += (a[0] * a[0] + a[1] * a[1]) + (a[2] * a[2] + a[3] * a[3]);
;                             if (row < TX) { const f32x4 g = *(const f32x4*)(gq + c); u32x2 w; w.x = cvt_pk_bf16(a[0] * g[0], a[1] * g[1]); w.y = cvt_pk_bf16(a[2] * g[2], a[3] * g[3]); *(u32x2*)(aqn + (size_t)row * 256 + c) = w; } }
.LBB0_1580:
.LBB0_1581:
	s_and_saveexec_b64 s[46:47], s[10:11]
	s_cbranch_execz .LBB0_1583
	v_ashrrev_i32_e32 v141, 31, v140
	v_lshl_add_u64 v[84:85], v[140:141], 2, s[54:55]
	v_mov_b32_e32 v88, v202
	v_mov_b32_e32 v89, v203
	v_mov_b32_e32 v90, v204
	v_mov_b32_e32 v91, v205
	v_mul_f32_e32 v84, v76, v88
	v_mul_f32_e32 v85, v77, v89
	v_lshl_add_u64 v[88:89], s[74:75], 0, v[80:81]
	v_cvt_pk_bf16_f32 v84, v84, v85
	v_mul_f32_e32 v85, v78, v90
	v_lshl_add_u64 v[88:89], v[140:141], 1, v[88:89]
	v_mul_f32_e32 v87, v79, v91
	v_cvt_pk_bf16_f32 v85, v85, v87
	global_store_dwordx2 v[88:89], v[84:85], off offset:32

; DEV unsigned cvt_pk_bf16(float lo, float hi) { unsigned r; asm volatile("v_cvt_pk_bf16_f32 %0, %1, %2" : "=v"(r) : "v"(lo), "v"(hi)); return r; }
;     DEV void operator()(const Acc& acc, const Unit& u, int wr, int wc, int fr, int fq, LAS unsigned char* misc) const {
;     ...
;                         if (isq) { sq += (a[0] * a[0] + a[1] * a[1]) + (a[2] * a[2] + a[3] * a[3]);
;                             if (row < TX) { const f32x4 g = *(const f32x4*)(gq + c); u32x2 w; w.x = cvt_pk_bf16(a[0] * g[0], a[1] * g[1]); w.y = cvt_pk_bf16(a[2] * g[2], a[3] * g[3]); *(u32x2*)(aqn + (size_t)row * 256 + c) = w; } }
.LBB0_1585:
	v_mul_f32_e32 v77, v77, v77
	v_mul_f32_e32 v73, v73, v73
	v_fmac_f32_e32 v77, v76, v76
	v_mul_f32_e32 v76, v79, v79
	v_fmac_f32_e32 v73, v72, v72
	v_mul_f32_e32 v72, v75, v75
	v_fmac_f32_e32 v76, v78, v78
	v_fmac_f32_e32 v72, v74, v74
	v_add_f32_e32 v76, v77, v76
	v_add_f32_e32 v72, v73, v72
	s_andn2_b64 vcc, exec, s[46:47]
	v_add_f32_e32 v72, v72, v76
	s_cbranch_vccnz .LBB0_1589
	s_and_saveexec_b64 s[46:47], s[10:11]
	s_cbranch_execz .LBB0_1588
	v_ashrrev_i32_e32 v141, 31, v140
	v_lshl_add_u64 v[74:75], v[140:141], 2, s[54:55]
	v_mov_b32_e32 v74, v206
	v_mov_b32_e32 v75, v207
	v_mov_b32_e32 v76, v208
	v_mov_b32_e32 v77, v209
	v_mul_f32_e32 v73, v68, v74
	v_mul_f32_e32 v74, v69, v75
	v_cvt_pk_bf16_f32 v74, v73, v74
	v_mul_f32_e32 v73, v70, v76
	v_mul_f32_e32 v75, v71, v77
	v_lshl_add_u64 v[76:77], s[74:75], 0, v[80:81]
	v_lshl_add_u64 v[76:77], v[140:141], 1, v[76:77]
	v_cvt_pk_bf16_f32 v75, v73, v75
	global_store_dwordx2 v[76:77], v[74:75], off offset:256

; DEV unsigned cvt_pk_bf16(float lo, float hi) { unsigned r; asm volatile("v_cvt_pk_bf16_f32 %0, %1, %2" : "=v"(r) : "v"(lo), "v"(hi)); return r; }
;     DEV void operator()(const Acc& acc, const Unit& u, int wr, int wc, int fr, int fq, LAS unsigned char* misc) const {
;     ...
;                     for (int n = 0; n < 2; ++n) { const int c = bj * 128 + wc * 32 + n * 16 + 4 * fq; const f32x4 a = acc[ai][bj][m][n];
;                         if (isq) { sq += (a[0] * a[0] + a[1] * a[1]) + (a[2] * a[2] + a[3] * a[3]);
;                             if (row < TX) { const f32x4 g = *(const f32x4*)(gq + c); u32x2 w; w.x = cvt_pk_bf16(a[0] * g[0], a[1] * g[1]); w.y = cvt_pk_bf16(a[2] * g[2], a[3] * g[3]); *(u32x2*)(aqn + (size_t)row * 256 + c) = w; } }
.LBB0_1593:
.LBB0_1594:
	s_and_saveexec_b64 s[46:47], s[10:11]
	s_cbranch_execz .LBB0_1596
	v_ashrrev_i32_e32 v141, 31, v140
	v_lshl_add_u64 v[68:69], v[140:141], 2, s[54:55]
	v_mov_b32_e32 v68, v210
	v_mov_b32_e32 v69, v211
	v_mov_b32_e32 v70, v212
	v_mov_b32_e32 v71, v213
	v_lshl_add_u64 v[74:75], s[74:75], 0, v[80:81]
	v_mul_f32_e32 v68, v64, v68
	v_mul_f32_e32 v69, v65, v69
	v_mul_f32_e32 v70, v66, v70
	v_mul_f32_e32 v71, v67, v71
	v_cvt_pk_bf16_f32 v68, v68, v69
	v_cvt_pk_bf16_f32 v69, v70, v71
	v_lshl_add_u64 v[70:71], v[140:141], 1, v[74:75]
	global_store_dwordx2 v[70:71], v[68:69], off offset:288

; DEV unsigned cvt_pk_bf16(float lo, float hi) { unsigned r; asm volatile("v_cvt_pk_bf16_f32 %0, %1, %2" : "=v"(r) : "v"(lo), "v"(hi)); return r; }
;     DEV void operator()(const Acc& acc, const Unit& u, int wr, int wc, int fr, int fq, LAS unsigned char* misc) const {
;     ...
;             for (int m = 0; m < 4; ++m) { const int rl = ai * 128 + wr * 64 + m * 16 + fr, row = rt + rl; float sq = 0.f;
; #pragma unroll
;                 for (int bj = 0; bj < 2; ++bj)
; #pragma unroll
;                     for (int n = 0; n < 2; ++n) { const int c = bj * 128 + wc * 32 + n * 16 + 4 * fq; const f32x4 a = acc[ai][bj][m][n];
;                         if (isq) { sq += (a[0] * a[0] + a[1] * a[1]) + (a[2] * a[2] + a[3] * a[3]);
;                             if (row < TX) { const f32x4 g = *(const f32x4*)(gq + c); u32x2 w; w.x = cvt_pk_bf16(a[0] * g[0], a[1] * g[1]); w.y = cvt_pk_bf16(a[2] * g[2], a[3] * g[3]); *(u32x2*)(aqn + (size_t)row * 256 + c) = w; } }
;                         else if (bj == 0) { sq += (a[0] * a[0] + a[1] * a[1]) + (a[2] * a[2] + a[3] * a[3]);
;                             const f32x4 g = *(const f32x4*)(gk + c); u32x2 w; w.x = cvt_pk_bf16(a[0] * g[0], a[1] * g[1]); w.y = cvt_pk_bf16(a[2] * g[2], a[3] * g[3]); *(u32x2*)(ckvn + (size_t)row * 128 + c) = w; }
;                         else if (wc == 0) { *(f32x4*)(kpe + (size_t)row * 32 + n * 16 + 4 * fq) = a; } }
.LBB0_1599:
	s_or_b64 exec, exec, s[10:11]
	v_add_u32_e32 v70, 0x80, v156
	v_add_u32_e32 v66, s19, v70
	v_ashrrev_i32_e32 v67, 31, v66
	s_waitcnt lgkmcnt(0)
	v_lshlrev_b64 v[64:65], 8, v[66:67]
	v_cmp_gt_i32_e64 s[10:11], s97, v66
	s_and_b64 vcc, exec, s[4:5]
	v_lshl_add_u64 v[68:69], s[68:69], 0, v[64:65]
	s_cbranch_vccnz .LBB0_1607
	v_ashrrev_i32_e32 v141, 31, v140
	v_lshl_add_u64 v[64:65], v[140:141], 2, s[50:51]
	v_mov_b32_e32 v72, v190
	v_mov_b32_e32 v73, v191
	v_mov_b32_e32 v74, v192
	v_mov_b32_e32 v75, v193
	v_lshl_add_u64 v[64:65], v[140:141], 1, v[68:69]
	v_mul_f32_e32 v71, v56, v72
	v_mul_f32_e32 v72, v57, v73
	v_mul_f32_e32 v73, v58, v74
	v_mul_f32_e32 v74, v59, v75
	v_cvt_pk_bf16_f32 v72, v71, v72
	v_cvt_pk_bf16_f32 v73, v73, v74
	global_store_dwordx2 v[64:65], v[72:73], off
	v_lshlrev_b64 v[64:65], 9, v[66:67]
	s_cbranch_execz .LBB0_1608
	s_and_b64 vcc, exec, s[4:5]
	s_cbranch_vccnz .LBB0_1611
.LBB0_1602:
	v_ashrrev_i32_e32 v141, 31, v140
	v_lshl_add_u64 v[72:73], v[140:141], 2, s[50:51]
	v_mov_b32_e32 v72, v194
	v_mov_b32_e32 v73, v195
	v_mov_b32_e32 v74, v196
	v_mov_b32_e32 v75, v197
	v_lshl_add_u64 v[68:69], v[140:141], 1, v[68:69]
	v_mul_f32_e32 v71, v60, v72
	v_mul_f32_e32 v72, v61, v73
	v_mul_f32_e32 v73, v62, v74
	v_mul_f32_e32 v74, v63, v75
	v_cvt_pk_bf16_f32 v72, v71, v72
	v_cvt_pk_bf16_f32 v73, v73, v74
	global_store_dwordx2 v[68:69], v[72:73], off offset:32
	s_cbranch_execz .LBB0_1612
	s_and_b64 vcc, exec, s[4:5]
	v_lshlrev_b64 v[66:67], 7, v[66:67]
	s_cbranch_vccnz .LBB0_1615

; DEV unsigned cvt_pk_bf16(float lo, float hi) { unsigned r; asm volatile("v_cvt_pk_bf16_f32 %0, %1, %2" : "=v"(r) : "v"(lo), "v"(hi)); return r; }
;     DEV void operator()(const Acc& acc, const Unit& u, int wr, int wc, int fr, int fq, LAS unsigned char* misc) const {
;     ...
;                     for (int n = 0; n < 2; ++n) { const int c = bj * 128 + wc * 32 + n * 16 + 4 * fq; const f32x4 a = acc[ai][bj][m][n];
;                         if (isq) { sq += (a[0] * a[0] + a[1] * a[1]) + (a[2] * a[2] + a[3] * a[3]);
;                             if (row < TX) { const f32x4 g = *(const f32x4*)(gq + c); u32x2 w; w.x = cvt_pk_bf16(a[0] * g[0], a[1] * g[1]); w.y = cvt_pk_bf16(a[2] * g[2], a[3] * g[3]); *(u32x2*)(aqn + (size_t)row * 256 + c) = w; } }
.LBB0_1608:
	s_and_saveexec_b64 s[46:47], s[10:11]
	s_cbranch_execz .LBB0_1610
	v_ashrrev_i32_e32 v141, 31, v140
	v_lshl_add_u64 v[72:73], v[140:141], 2, s[54:55]
	v_mov_b32_e32 v72, v198
	v_mov_b32_e32 v73, v199
	v_mov_b32_e32 v74, v200
	v_mov_b32_e32 v75, v201
	v_mul_f32_e32 v71, v56, v72
	v_mul_f32_e32 v72, v57, v73
	v_cvt_pk_bf16_f32 v72, v71, v72
	v_mul_f32_e32 v71, v58, v74
	v_mul_f32_e32 v73, v59, v75
	v_lshl_add_u64 v[74:75], s[74:75], 0, v[64:65]
	v_lshl_add_u64 v[74:75], v[140:141], 1, v[74:75]
	v_cvt_pk_bf16_f32 v73, v71, v73
	global_store_dwordx2 v[74:75], v[72:73], off

; DEV unsigned cvt_pk_bf16(float lo, float hi) { unsigned r; asm volatile("v_cvt_pk_bf16_f32 %0, %1, %2" : "=v"(r) : "v"(lo), "v"(hi)); return r; }
;     DEV void operator()(const Acc& acc, const Unit& u, int wr, int wc, int fr, int fq, LAS unsigned char* misc) const {
;     ...
;                     for (int n = 0; n < 2; ++n) { const int c = bj * 128 + wc * 32 + n * 16 + 4 * fq; const f32x4 a = acc[ai][bj][m][n];
;                         if (isq) { sq += (a[0] * a[0] + a[1] * a[1]) + (a[2] * a[2] + a[3] * a[3]);
;                             if (row < TX) { const f32x4 g = *(const f32x4*)(gq + c); u32x2 w; w.x = cvt_pk_bf16(a[0] * g[0], a[1] * g[1]); w.y = cvt_pk_bf16(a[2] * g[2], a[3] * g[3]); *(u32x2*)(aqn + (size_t)row * 256 + c) = w; } }
.LBB0_1611:
.LBB0_1612:
	s_and_saveexec_b64 s[46:47], s[10:11]
	s_cbranch_execz .LBB0_1614
	v_ashrrev_i32_e32 v141, 31, v140
	v_lshl_add_u64 v[68:69], v[140:141], 2, s[54:55]
	v_mov_b32_e32 v72, v202
	v_mov_b32_e32 v73, v203
	v_mov_b32_e32 v74, v204
	v_mov_b32_e32 v75, v205
	v_mul_f32_e32 v68, v60, v72
	v_mul_f32_e32 v69, v61, v73
	v_lshl_add_u64 v[72:73], s[74:75], 0, v[64:65]
	v_cvt_pk_bf16_f32 v68, v68, v69
	v_mul_f32_e32 v69, v62, v74
	v_lshl_add_u64 v[72:73], v[140:141], 1, v[72:73]
	v_mul_f32_e32 v71, v63, v75
	v_cvt_pk_bf16_f32 v69, v69, v71
	global_store_dwordx2 v[72:73], v[68:69], off offset:32

; DEV unsigned cvt_pk_bf16(float lo, float hi) { unsigned r; asm volatile("v_cvt_pk_bf16_f32 %0, %1, %2" : "=v"(r) : "v"(lo), "v"(hi)); return r; }
;     DEV void operator()(const Acc& acc, const Unit& u, int wr, int wc, int fr, int fq, LAS unsigned char* misc) const {
;     ...
;                         if (isq) { sq += (a[0] * a[0] + a[1] * a[1]) + (a[2] * a[2] + a[3] * a[3]);
;                             if (row < TX) { const f32x4 g = *(const f32x4*)(gq + c); u32x2 w; w.x = cvt_pk_bf16(a[0] * g[0], a[1] * g[1]); w.y = cvt_pk_bf16(a[2] * g[2], a[3] * g[3]); *(u32x2*)(aqn + (size_t)row * 256 + c) = w; } }
.LBB0_1616:
	v_mul_f32_e32 v61, v61, v61
	v_mul_f32_e32 v57, v57, v57
	v_fmac_f32_e32 v61, v60, v60
	v_mul_f32_e32 v60, v63, v63
	v_fmac_f32_e32 v57, v56, v56
	v_mul_f32_e32 v56, v59, v59
	v_fmac_f32_e32 v60, v62, v62
	v_fmac_f32_e32 v56, v58, v58
	v_add_f32_e32 v60, v61, v60
	v_add_f32_e32 v56, v57, v56
	s_andn2_b64 vcc, exec, s[46:47]
	v_add_f32_e32 v56, v56, v60
	s_cbranch_vccnz .LBB0_1620
	s_and_saveexec_b64 s[46:47], s[10:11]
	s_cbranch_execz .LBB0_1619
	v_ashrrev_i32_e32 v141, 31, v140
	v_lshl_add_u64 v[58:59], v[140:141], 2, s[54:55]
	v_mov_b32_e32 v58, v206
	v_mov_b32_e32 v59, v207
	v_mov_b32_e32 v60, v208
	v_mov_b32_e32 v61, v209
	v_mul_f32_e32 v57, v52, v58
	v_mul_f32_e32 v58, v53, v59
	v_cvt_pk_bf16_f32 v58, v57, v58
	v_mul_f32_e32 v57, v54, v60
	v_mul_f32_e32 v59, v55, v61
	v_lshl_add_u64 v[60:61], s[74:75], 0, v[64:65]
	v_lshl_add_u64 v[60:61], v[140:141], 1, v[60:61]
	v_cvt_pk_bf16_f32 v59, v57, v59
	global_store_dwordx2 v[60:61], v[58:59], off offset:256

; DEV unsigned cvt_pk_bf16(float lo, float hi) { unsigned r; asm volatile("v_cvt_pk_bf16_f32 %0, %1, %2" : "=v"(r) : "v"(lo), "v"(hi)); return r; }
;     DEV void operator()(const Acc& acc, const Unit& u, int wr, int wc, int fr, int fq, LAS unsigned char* misc) const {
;     ...
;                     for (int n = 0; n < 2; ++n) { const int c = bj * 128 + wc * 32 + n * 16 + 4 * fq; const f32x4 a = acc[ai][bj][m][n];
;                         if (isq) { sq += (a[0] * a[0] + a[1] * a[1]) + (a[2] * a[2] + a[3] * a[3]);
;                             if (row < TX) { const f32x4 g = *(const f32x4*)(gq + c); u32x2 w; w.x = cvt_pk_bf16(a[0] * g[0], a[1] * g[1]); w.y = cvt_pk_bf16(a[2] * g[2], a[3] * g[3]); *(u32x2*)(aqn + (size_t)row * 256 + c) = w; } }
.LBB0_1624:
.LBB0_1625:
	s_and_saveexec_b64 s[46:47], s[10:11]
	s_cbranch_execz .LBB0_1627
	v_ashrrev_i32_e32 v141, 31, v140
	v_lshl_add_u64 v[52:53], v[140:141], 2, s[54:55]
	v_mov_b32_e32 v52, v210
	v_mov_b32_e32 v53, v211
	v_mov_b32_e32 v54, v212
	v_mov_b32_e32 v55, v213
	v_lshl_add_u64 v[58:59], s[74:75], 0, v[64:65]
	v_mul_f32_e32 v52, v48, v52
	v_mul_f32_e32 v53, v49, v53
	v_mul_f32_e32 v54, v50, v54
	v_mul_f32_e32 v55, v51, v55
	v_cvt_pk_bf16_f32 v52, v52, v53
	v_cvt_pk_bf16_f32 v53, v54, v55
	v_lshl_add_u64 v[54:55], v[140:141], 1, v[58:59]
	global_store_dwordx2 v[54:55], v[52:53], off offset:288

; DEV unsigned cvt_pk_bf16(float lo, float hi) { unsigned r; asm volatile("v_cvt_pk_bf16_f32 %0, %1, %2" : "=v"(r) : "v"(lo), "v"(hi)); return r; }
;     DEV void operator()(const Acc& acc, const Unit& u, int wr, int wc, int fr, int fq, LAS unsigned char* misc) const {
;     ...
;             for (int m = 0; m < 4; ++m) { const int rl = ai * 128 + wr * 64 + m * 16 + fr, row = rt + rl; float sq = 0.f;
; #pragma unroll
;                 for (int bj = 0; bj < 2; ++bj)
; #pragma unroll
;                     for (int n = 0; n < 2; ++n) { const int c = bj * 128 + wc * 32 + n * 16 + 4 * fq; const f32x4 a = acc[ai][bj][m][n];
;                         if (isq) { sq += (a[0] * a[0] + a[1] * a[1]) + (a[2] * a[2] + a[3] * a[3]);
;                             if (row < TX) { const f32x4 g = *(const f32x4*)(gq + c); u32x2 w; w.x = cvt_pk_bf16(a[0] * g[0], a[1] * g[1]); w.y = cvt_pk_bf16(a[2] * g[2], a[3] * g[3]); *(u32x2*)(aqn + (size_t)row * 256 + c) = w; } }
;                         else if (bj == 0) { sq += (a[0] * a[0] + a[1] * a[1]) + (a[2] * a[2] + a[3] * a[3]);
;                             const f32x4 g = *(const f32x4*)(gk + c); u32x2 w; w.x = cvt_pk_bf16(a[0] * g[0], a[1] * g[1]); w.y = cvt_pk_bf16(a[2] * g[2], a[3] * g[3]); *(u32x2*)(ckvn + (size_t)row * 128 + c) = w; }
;                         else if (wc == 0) { *(f32x4*)(kpe + (size_t)row * 32 + n * 16 + 4 * fq) = a; } }
.LBB0_1630:
	s_or_b64 exec, exec, s[10:11]
	v_add_u32_e32 v54, 0x90, v156
	v_add_u32_e32 v50, s19, v54
	v_ashrrev_i32_e32 v51, 31, v50
	s_waitcnt lgkmcnt(0)
	v_lshlrev_b64 v[48:49], 8, v[50:51]
	v_cmp_gt_i32_e64 s[10:11], s97, v50
	s_and_b64 vcc, exec, s[4:5]
	v_lshl_add_u64 v[52:53], s[68:69], 0, v[48:49]
	s_cbranch_vccnz .LBB0_1638
	v_ashrrev_i32_e32 v141, 31, v140
	v_lshl_add_u64 v[48:49], v[140:141], 2, s[50:51]
	v_mov_b32_e32 v56, v190
	v_mov_b32_e32 v57, v191
	v_mov_b32_e32 v58, v192
	v_mov_b32_e32 v59, v193
	v_lshl_add_u64 v[48:49], v[140:141], 1, v[52:53]
	v_mul_f32_e32 v55, v40, v56
	v_mul_f32_e32 v56, v41, v57
	v_mul_f32_e32 v57, v42, v58
	v_mul_f32_e32 v58, v43, v59
	v_cvt_pk_bf16_f32 v56, v55, v56
	v_cvt_pk_bf16_f32 v57, v57, v58
	global_store_dwordx2 v[48:49], v[56:57], off
	v_lshlrev_b64 v[48:49], 9, v[50:51]
	s_cbranch_execz .LBB0_1639
	s_and_b64 vcc, exec, s[4:5]
	s_cbranch_vccnz .LBB0_1642
.LBB0_1633:
	v_ashrrev_i32_e32 v141, 31, v140
	v_lshl_add_u64 v[56:57], v[140:141], 2, s[50:51]
	v_mov_b32_e32 v56, v194
	v_mov_b32_e32 v57, v195
	v_mov_b32_e32 v58, v196
	v_mov_b32_e32 v59, v197
	v_lshl_add_u64 v[52:53], v[140:141], 1, v[52:53]
	v_mul_f32_e32 v55, v44, v56
	v_mul_f32_e32 v56, v45, v57
	v_mul_f32_e32 v57, v46, v58
	v_mul_f32_e32 v58, v47, v59
	v_cvt_pk_bf16_f32 v56, v55, v56
	v_cvt_pk_bf16_f32 v57, v57, v58
	global_store_dwordx2 v[52:53], v[56:57], off offset:32
	s_cbranch_execz .LBB0_1643
	s_and_b64 vcc, exec, s[4:5]
	v_lshlrev_b64 v[50:51], 7, v[50:51]
	s_cbranch_vccnz .LBB0_1646

; DEV unsigned cvt_pk_bf16(float lo, float hi) { unsigned r; asm volatile("v_cvt_pk_bf16_f32 %0, %1, %2" : "=v"(r) : "v"(lo), "v"(hi)); return r; }
;     DEV void operator()(const Acc& acc, const Unit& u, int wr, int wc, int fr, int fq, LAS unsigned char* misc) const {
;     ...
;                     for (int n = 0; n < 2; ++n) { const int c = bj * 128 + wc * 32 + n * 16 + 4 * fq; const f32x4 a = acc[ai][bj][m][n];
;                         if (isq) { sq += (a[0] * a[0] + a[1] * a[1]) + (a[2] * a[2] + a[3] * a[3]);
;                             if (row < TX) { const f32x4 g = *(const f32x4*)(gq + c); u32x2 w; w.x = cvt_pk_bf16(a[0] * g[0], a[1] * g[1]); w.y = cvt_pk_bf16(a[2] * g[2], a[3] * g[3]); *(u32x2*)(aqn + (size_t)row * 256 + c) = w; } }
.LBB0_1639:
	s_and_saveexec_b64 s[46:47], s[10:11]
	s_cbranch_execz .LBB0_1641
	v_ashrrev_i32_e32 v141, 31, v140
	v_lshl_add_u64 v[56:57], v[140:141], 2, s[54:55]
	v_mov_b32_e32 v56, v198
	v_mov_b32_e32 v57, v199
	v_mov_b32_e32 v58, v200
	v_mov_b32_e32 v59, v201
	v_mul_f32_e32 v55, v40, v56
	v_mul_f32_e32 v56, v41, v57
	v_cvt_pk_bf16_f32 v56, v55, v56
	v_mul_f32_e32 v55, v42, v58
	v_mul_f32_e32 v57, v43, v59
	v_lshl_add_u64 v[58:59], s[74:75], 0, v[48:49]
	v_lshl_add_u64 v[58:59], v[140:141], 1, v[58:59]
	v_cvt_pk_bf16_f32 v57, v55, v57
	global_store_dwordx2 v[58:59], v[56:57], off

; DEV unsigned cvt_pk_bf16(float lo, float hi) { unsigned r; asm volatile("v_cvt_pk_bf16_f32 %0, %1, %2" : "=v"(r) : "v"(lo), "v"(hi)); return r; }
;     DEV void operator()(const Acc& acc, const Unit& u, int wr, int wc, int fr, int fq, LAS unsigned char* misc) const {
;     ...
;                     for (int n = 0; n < 2; ++n) { const int c = bj * 128 + wc * 32 + n * 16 + 4 * fq; const f32x4 a = acc[ai][bj][m][n];
;                         if (isq) { sq += (a[0] * a[0] + a[1] * a[1]) + (a[2] * a[2] + a[3] * a[3]);
;                             if (row < TX) { const f32x4 g = *(const f32x4*)(gq + c); u32x2 w; w.x = cvt_pk_bf16(a[0] * g[0], a[1] * g[1]); w.y = cvt_pk_bf16(a[2] * g[2], a[3] * g[3]); *(u32x2*)(aqn + (size_t)row * 256 + c) = w; } }
.LBB0_1642:
.LBB0_1643:
	s_and_saveexec_b64 s[46:47], s[10:11]
	s_cbranch_execz .LBB0_1645
	v_ashrrev_i32_e32 v141, 31, v140
	v_lshl_add_u64 v[52:53], v[140:141], 2, s[54:55]
	v_mov_b32_e32 v56, v202
	v_mov_b32_e32 v57, v203
	v_mov_b32_e32 v58, v204
	v_mov_b32_e32 v59, v205
	v_mul_f32_e32 v52, v44, v56
	v_mul_f32_e32 v53, v45, v57
	v_lshl_add_u64 v[56:57], s[74:75], 0, v[48:49]
	v_cvt_pk_bf16_f32 v52, v52, v53
	v_mul_f32_e32 v53, v46, v58
	v_lshl_add_u64 v[56:57], v[140:141], 1, v[56:57]
	v_mul_f32_e32 v55, v47, v59
	v_cvt_pk_bf16_f32 v53, v53, v55
	global_store_dwordx2 v[56:57], v[52:53], off offset:32

; DEV unsigned cvt_pk_bf16(float lo, float hi) { unsigned r; asm volatile("v_cvt_pk_bf16_f32 %0, %1, %2" : "=v"(r) : "v"(lo), "v"(hi)); return r; }
;     DEV void operator()(const Acc& acc, const Unit& u, int wr, int wc, int fr, int fq, LAS unsigned char* misc) const {
;     ...
;                         if (isq) { sq += (a[0] * a[0] + a[1] * a[1]) + (a[2] * a[2] + a[3] * a[3]);
;                             if (row < TX) { const f32x4 g = *(const f32x4*)(gq + c); u32x2 w; w.x = cvt_pk_bf16(a[0] * g[0], a[1] * g[1]); w.y = cvt_pk_bf16(a[2] * g[2], a[3] * g[3]); *(u32x2*)(aqn + (size_t)row * 256 + c) = w; } }
.LBB0_1647:
	v_mul_f32_e32 v45, v45, v45
	v_mul_f32_e32 v41, v41, v41
	v_fmac_f32_e32 v45, v44, v44
	v_mul_f32_e32 v44, v47, v47
	v_fmac_f32_e32 v41, v40, v40
	v_mul_f32_e32 v40, v43, v43
	v_fmac_f32_e32 v44, v46, v46
	v_fmac_f32_e32 v40, v42, v42
	v_add_f32_e32 v44, v45, v44
	v_add_f32_e32 v40, v41, v40
	s_andn2_b64 vcc, exec, s[46:47]
	v_add_f32_e32 v40, v40, v44
	s_cbranch_vccnz .LBB0_1651
	s_and_saveexec_b64 s[46:47], s[10:11]
	s_cbranch_execz .LBB0_1650
	v_ashrrev_i32_e32 v141, 31, v140
	v_lshl_add_u64 v[42:43], v[140:141], 2, s[54:55]
	v_mov_b32_e32 v42, v206
	v_mov_b32_e32 v43, v207
	v_mov_b32_e32 v44, v208
	v_mov_b32_e32 v45, v209
	v_mul_f32_e32 v41, v36, v42
	v_mul_f32_e32 v42, v37, v43
	v_cvt_pk_bf16_f32 v42, v41, v42
	v_mul_f32_e32 v41, v38, v44
	v_mul_f32_e32 v43, v39, v45
	v_lshl_add_u64 v[44:45], s[74:75], 0, v[48:49]
	v_lshl_add_u64 v[44:45], v[140:141], 1, v[44:45]
	v_cvt_pk_bf16_f32 v43, v41, v43
	global_store_dwordx2 v[44:45], v[42:43], off offset:256

; DEV unsigned cvt_pk_bf16(float lo, float hi) { unsigned r; asm volatile("v_cvt_pk_bf16_f32 %0, %1, %2" : "=v"(r) : "v"(lo), "v"(hi)); return r; }
;     DEV void operator()(const Acc& acc, const Unit& u, int wr, int wc, int fr, int fq, LAS unsigned char* misc) const {
;     ...
;                     for (int n = 0; n < 2; ++n) { const int c = bj * 128 + wc * 32 + n * 16 + 4 * fq; const f32x4 a = acc[ai][bj][m][n];
;                         if (isq) { sq += (a[0] * a[0] + a[1] * a[1]) + (a[2] * a[2] + a[3] * a[3]);
;                             if (row < TX) { const f32x4 g = *(const f32x4*)(gq + c); u32x2 w; w.x = cvt_pk_bf16(a[0] * g[0], a[1] * g[1]); w.y = cvt_pk_bf16(a[2] * g[2], a[3] * g[3]); *(u32x2*)(aqn + (size_t)row * 256 + c) = w; } }
.LBB0_1655:
.LBB0_1656:
	s_and_saveexec_b64 s[46:47], s[10:11]
	s_cbranch_execz .LBB0_1658
	v_ashrrev_i32_e32 v141, 31, v140
	v_lshl_add_u64 v[36:37], v[140:141], 2, s[54:55]
	v_mov_b32_e32 v36, v210
	v_mov_b32_e32 v37, v211
	v_mov_b32_e32 v38, v212
	v_mov_b32_e32 v39, v213
	v_lshl_add_u64 v[42:43], s[74:75], 0, v[48:49]
	v_mul_f32_e32 v36, v32, v36
	v_mul_f32_e32 v37, v33, v37
	v_mul_f32_e32 v38, v34, v38
	v_mul_f32_e32 v39, v35, v39
	v_cvt_pk_bf16_f32 v36, v36, v37
	v_cvt_pk_bf16_f32 v37, v38, v39
	v_lshl_add_u64 v[38:39], v[140:141], 1, v[42:43]
	global_store_dwordx2 v[38:39], v[36:37], off offset:288

; DEV unsigned cvt_pk_bf16(float lo, float hi) { unsigned r; asm volatile("v_cvt_pk_bf16_f32 %0, %1, %2" : "=v"(r) : "v"(lo), "v"(hi)); return r; }
;     DEV void operator()(const Acc& acc, const Unit& u, int wr, int wc, int fr, int fq, LAS unsigned char* misc) const {
;     ...
;             for (int m = 0; m < 4; ++m) { const int rl = ai * 128 + wr * 64 + m * 16 + fr, row = rt + rl; float sq = 0.f;
; #pragma unroll
;                 for (int bj = 0; bj < 2; ++bj)
; #pragma unroll
;                     for (int n = 0; n < 2; ++n) { const int c = bj * 128 + wc * 32 + n * 16 + 4 * fq; const f32x4 a = acc[ai][bj][m][n];
;                         if (isq) { sq += (a[0] * a[0] + a[1] * a[1]) + (a[2] * a[2] + a[3] * a[3]);
;                             if (row < TX) { const f32x4 g = *(const f32x4*)(gq + c); u32x2 w; w.x = cvt_pk_bf16(a[0] * g[0], a[1] * g[1]); w.y = cvt_pk_bf16(a[2] * g[2], a[3] * g[3]); *(u32x2*)(aqn + (size_t)row * 256 + c) = w; } }
;                         else if (bj == 0) { sq += (a[0] * a[0] + a[1] * a[1]) + (a[2] * a[2] + a[3] * a[3]);
;                             const f32x4 g = *(const f32x4*)(gk + c); u32x2 w; w.x = cvt_pk_bf16(a[0] * g[0], a[1] * g[1]); w.y = cvt_pk_bf16(a[2] * g[2], a[3] * g[3]); *(u32x2*)(ckvn + (size_t)row * 128 + c) = w; }
;                         else if (wc == 0) { *(f32x4*)(kpe + (size_t)row * 32 + n * 16 + 4 * fq) = a; } }
.LBB0_1661:
	s_or_b64 exec, exec, s[10:11]
	v_add_u32_e32 v38, 0xa0, v156
	v_add_u32_e32 v34, s19, v38
	v_ashrrev_i32_e32 v35, 31, v34
	s_waitcnt lgkmcnt(0)
	v_lshlrev_b64 v[32:33], 8, v[34:35]
	v_cmp_gt_i32_e64 s[10:11], s97, v34
	s_and_b64 vcc, exec, s[4:5]
	v_lshl_add_u64 v[36:37], s[68:69], 0, v[32:33]
	s_cbranch_vccnz .LBB0_1669
	v_ashrrev_i32_e32 v141, 31, v140
	v_lshl_add_u64 v[32:33], v[140:141], 2, s[50:51]
	v_mov_b32_e32 v40, v190
	v_mov_b32_e32 v41, v191
	v_mov_b32_e32 v42, v192
	v_mov_b32_e32 v43, v193
	v_lshl_add_u64 v[32:33], v[140:141], 1, v[36:37]
	v_mul_f32_e32 v39, v24, v40
	v_mul_f32_e32 v40, v25, v41
	v_mul_f32_e32 v41, v26, v42
	v_mul_f32_e32 v42, v27, v43
	v_cvt_pk_bf16_f32 v40, v39, v40
	v_cvt_pk_bf16_f32 v41, v41, v42
	global_store_dwordx2 v[32:33], v[40:41], off
	v_lshlrev_b64 v[32:33], 9, v[34:35]
	s_cbranch_execz .LBB0_1670
	s_and_b64 vcc, exec, s[4:5]
	s_cbranch_vccnz .LBB0_1673
.LBB0_1664:
	v_ashrrev_i32_e32 v141, 31, v140
	v_lshl_add_u64 v[40:41], v[140:141], 2, s[50:51]
	v_mov_b32_e32 v40, v194
	v_mov_b32_e32 v41, v195
	v_mov_b32_e32 v42, v196
	v_mov_b32_e32 v43, v197
	v_lshl_add_u64 v[36:37], v[140:141], 1, v[36:37]
	v_mul_f32_e32 v39, v28, v40
	v_mul_f32_e32 v40, v29, v41
	v_mul_f32_e32 v41, v30, v42
	v_mul_f32_e32 v42, v31, v43
	v_cvt_pk_bf16_f32 v40, v39, v40
	v_cvt_pk_bf16_f32 v41, v41, v42
	global_store_dwordx2 v[36:37], v[40:41], off offset:32
	s_cbranch_execz .LBB0_1674
	s_and_b64 vcc, exec, s[4:5]
	v_lshlrev_b64 v[34:35], 7, v[34:35]
	s_cbranch_vccnz .LBB0_1677

; DEV unsigned cvt_pk_bf16(float lo, float hi) { unsigned r; asm volatile("v_cvt_pk_bf16_f32 %0, %1, %2" : "=v"(r) : "v"(lo), "v"(hi)); return r; }
;     DEV void operator()(const Acc& acc, const Unit& u, int wr, int wc, int fr, int fq, LAS unsigned char* misc) const {
;     ...
;                     for (int n = 0; n < 2; ++n) { const int c = bj * 128 + wc * 32 + n * 16 + 4 * fq; const f32x4 a = acc[ai][bj][m][n];
;                         if (isq) { sq += (a[0] * a[0] + a[1] * a[1]) + (a[2] * a[2] + a[3] * a[3]);
;                             if (row < TX) { const f32x4 g = *(const f32x4*)(gq + c); u32x2 w; w.x = cvt_pk_bf16(a[0] * g[0], a[1] * g[1]); w.y = cvt_pk_bf16(a[2] * g[2], a[3] * g[3]); *(u32x2*)(aqn + (size_t)row * 256 + c) = w; } }
.LBB0_1670:
	s_and_saveexec_b64 s[46:47], s[10:11]
	s_cbranch_execz .LBB0_1672
	v_ashrrev_i32_e32 v141, 31, v140
	v_lshl_add_u64 v[40:41], v[140:141], 2, s[54:55]
	v_mov_b32_e32 v40, v198
	v_mov_b32_e32 v41, v199
	v_mov_b32_e32 v42, v200
	v_mov_b32_e32 v43, v201
	v_mul_f32_e32 v39, v24, v40
	v_mul_f32_e32 v40, v25, v41
	v_cvt_pk_bf16_f32 v40, v39, v40
	v_mul_f32_e32 v39, v26, v42
	v_mul_f32_e32 v41, v27, v43
	v_lshl_add_u64 v[42:43], s[74:75], 0, v[32:33]
	v_lshl_add_u64 v[42:43], v[140:141], 1, v[42:43]
	v_cvt_pk_bf16_f32 v41, v39, v41
	global_store_dwordx2 v[42:43], v[40:41], off

; DEV unsigned cvt_pk_bf16(float lo, float hi) { unsigned r; asm volatile("v_cvt_pk_bf16_f32 %0, %1, %2" : "=v"(r) : "v"(lo), "v"(hi)); return r; }
;     DEV void operator()(const Acc& acc, const Unit& u, int wr, int wc, int fr, int fq, LAS unsigned char* misc) const {
;     ...
;                     for (int n = 0; n < 2; ++n) { const int c = bj * 128 + wc * 32 + n * 16 + 4 * fq; const f32x4 a = acc[ai][bj][m][n];
;                         if (isq) { sq += (a[0] * a[0] + a[1] * a[1]) + (a[2] * a[2] + a[3] * a[3]);
;                             if (row < TX) { const f32x4 g = *(const f32x4*)(gq + c); u32x2 w; w.x = cvt_pk_bf16(a[0] * g[0], a[1] * g[1]); w.y = cvt_pk_bf16(a[2] * g[2], a[3] * g[3]); *(u32x2*)(aqn + (size_t)row * 256 + c) = w; } }
.LBB0_1673:
.LBB0_1674:
	s_and_saveexec_b64 s[46:47], s[10:11]
	s_cbranch_execz .LBB0_1676
	v_ashrrev_i32_e32 v141, 31, v140
	v_lshl_add_u64 v[36:37], v[140:141], 2, s[54:55]
	v_mov_b32_e32 v40, v202
	v_mov_b32_e32 v41, v203
	v_mov_b32_e32 v42, v204
	v_mov_b32_e32 v43, v205
	v_mul_f32_e32 v36, v28, v40
	v_mul_f32_e32 v37, v29, v41
	v_lshl_add_u64 v[40:41], s[74:75], 0, v[32:33]
	v_cvt_pk_bf16_f32 v36, v36, v37
	v_mul_f32_e32 v37, v30, v42
	v_lshl_add_u64 v[40:41], v[140:141], 1, v[40:41]
	v_mul_f32_e32 v39, v31, v43
	v_cvt_pk_bf16_f32 v37, v37, v39
	global_store_dwordx2 v[40:41], v[36:37], off offset:32

; DEV unsigned cvt_pk_bf16(float lo, float hi) { unsigned r; asm volatile("v_cvt_pk_bf16_f32 %0, %1, %2" : "=v"(r) : "v"(lo), "v"(hi)); return r; }
;     DEV void operator()(const Acc& acc, const Unit& u, int wr, int wc, int fr, int fq, LAS unsigned char* misc) const {
;     ...
;                         if (isq) { sq += (a[0] * a[0] + a[1] * a[1]) + (a[2] * a[2] + a[3] * a[3]);
;                             if (row < TX) { const f32x4 g = *(const f32x4*)(gq + c); u32x2 w; w.x = cvt_pk_bf16(a[0] * g[0], a[1] * g[1]); w.y = cvt_pk_bf16(a[2] * g[2], a[3] * g[3]); *(u32x2*)(aqn + (size_t)row * 256 + c) = w; } }
.LBB0_1678:
	v_mul_f32_e32 v29, v29, v29
	v_mul_f32_e32 v25, v25, v25
	v_fmac_f32_e32 v29, v28, v28
	v_mul_f32_e32 v28, v31, v31
	v_fmac_f32_e32 v25, v24, v24
	v_mul_f32_e32 v24, v27, v27
	v_fmac_f32_e32 v28, v30, v30
	v_fmac_f32_e32 v24, v26, v26
	v_add_f32_e32 v28, v29, v28
	v_add_f32_e32 v24, v25, v24
	s_andn2_b64 vcc, exec, s[46:47]
	v_add_f32_e32 v24, v24, v28
	s_cbranch_vccnz .LBB0_1682
	s_and_saveexec_b64 s[46:47], s[10:11]
	s_cbranch_execz .LBB0_1681
	v_ashrrev_i32_e32 v141, 31, v140
	v_lshl_add_u64 v[26:27], v[140:141], 2, s[54:55]
	v_mov_b32_e32 v26, v206
	v_mov_b32_e32 v27, v207
	v_mov_b32_e32 v28, v208
	v_mov_b32_e32 v29, v209
	v_mul_f32_e32 v25, v20, v26
	v_mul_f32_e32 v26, v21, v27
	v_cvt_pk_bf16_f32 v26, v25, v26
	v_mul_f32_e32 v25, v22, v28
	v_mul_f32_e32 v27, v23, v29
	v_lshl_add_u64 v[28:29], s[74:75], 0, v[32:33]
	v_lshl_add_u64 v[28:29], v[140:141], 1, v[28:29]
	v_cvt_pk_bf16_f32 v27, v25, v27
	global_store_dwordx2 v[28:29], v[26:27], off offset:256

; DEV unsigned cvt_pk_bf16(float lo, float hi) { unsigned r; asm volatile("v_cvt_pk_bf16_f32 %0, %1, %2" : "=v"(r) : "v"(lo), "v"(hi)); return r; }
;     DEV void operator()(const Acc& acc, const Unit& u, int wr, int wc, int fr, int fq, LAS unsigned char* misc) const {
;     ...
;                     for (int n = 0; n < 2; ++n) { const int c = bj * 128 + wc * 32 + n * 16 + 4 * fq; const f32x4 a = acc[ai][bj][m][n];
;                         if (isq) { sq += (a[0] * a[0] + a[1] * a[1]) + (a[2] * a[2] + a[3] * a[3]);
;                             if (row < TX) { const f32x4 g = *(const f32x4*)(gq + c); u32x2 w; w.x = cvt_pk_bf16(a[0] * g[0], a[1] * g[1]); w.y = cvt_pk_bf16(a[2] * g[2], a[3] * g[3]); *(u32x2*)(aqn + (size_t)row * 256 + c) = w; } }
.LBB0_1686:
.LBB0_1687:
	s_and_saveexec_b64 s[46:47], s[10:11]
	s_cbranch_execz .LBB0_1689
	v_ashrrev_i32_e32 v141, 31, v140
	v_lshl_add_u64 v[20:21], v[140:141], 2, s[54:55]
	v_mov_b32_e32 v20, v210
	v_mov_b32_e32 v21, v211
	v_mov_b32_e32 v22, v212
	v_mov_b32_e32 v23, v213
	v_lshl_add_u64 v[26:27], s[74:75], 0, v[32:33]
	v_mul_f32_e32 v20, v16, v20
	v_mul_f32_e32 v21, v17, v21
	v_mul_f32_e32 v22, v18, v22
	v_mul_f32_e32 v23, v19, v23
	v_cvt_pk_bf16_f32 v20, v20, v21
	v_cvt_pk_bf16_f32 v21, v22, v23
	v_lshl_add_u64 v[22:23], v[140:141], 1, v[26:27]
	global_store_dwordx2 v[22:23], v[20:21], off offset:288

; DEV unsigned cvt_pk_bf16(float lo, float hi) { unsigned r; asm volatile("v_cvt_pk_bf16_f32 %0, %1, %2" : "=v"(r) : "v"(lo), "v"(hi)); return r; }
;     DEV void operator()(const Acc& acc, const Unit& u, int wr, int wc, int fr, int fq, LAS unsigned char* misc) const {
;     ...
;             for (int m = 0; m < 4; ++m) { const int rl = ai * 128 + wr * 64 + m * 16 + fr, row = rt + rl; float sq = 0.f;
; #pragma unroll
;                 for (int bj = 0; bj < 2; ++bj)
; #pragma unroll
;                     for (int n = 0; n < 2; ++n) { const int c = bj * 128 + wc * 32 + n * 16 + 4 * fq; const f32x4 a = acc[ai][bj][m][n];
;                         if (isq) { sq += (a[0] * a[0] + a[1] * a[1]) + (a[2] * a[2] + a[3] * a[3]);
;                             if (row < TX) { const f32x4 g = *(const f32x4*)(gq + c); u32x2 w; w.x = cvt_pk_bf16(a[0] * g[0], a[1] * g[1]); w.y = cvt_pk_bf16(a[2] * g[2], a[3] * g[3]); *(u32x2*)(aqn + (size_t)row * 256 + c) = w; } }
;                         else if (bj == 0) { sq += (a[0] * a[0] + a[1] * a[1]) + (a[2] * a[2] + a[3] * a[3]);
;                             const f32x4 g = *(const f32x4*)(gk + c); u32x2 w; w.x = cvt_pk_bf16(a[0] * g[0], a[1] * g[1]); w.y = cvt_pk_bf16(a[2] * g[2], a[3] * g[3]); *(u32x2*)(ckvn + (size_t)row * 128 + c) = w; }
;                         else if (wc == 0) { *(f32x4*)(kpe + (size_t)row * 32 + n * 16 + 4 * fq) = a; } }
.LBB0_1692:
	s_or_b64 exec, exec, s[10:11]
	v_add_u32_e32 v22, 0xb0, v156
	v_add_u32_e32 v18, s19, v22
	v_ashrrev_i32_e32 v19, 31, v18
	s_waitcnt lgkmcnt(0)
	v_lshlrev_b64 v[16:17], 8, v[18:19]
	v_cmp_gt_i32_e64 s[10:11], s97, v18
	s_and_b64 vcc, exec, s[4:5]
	v_lshl_add_u64 v[20:21], s[68:69], 0, v[16:17]
	s_cbranch_vccnz .LBB0_1700
	v_ashrrev_i32_e32 v141, 31, v140
	v_lshl_add_u64 v[16:17], v[140:141], 2, s[50:51]
	v_mov_b32_e32 v24, v190
	v_mov_b32_e32 v25, v191
	v_mov_b32_e32 v26, v192
	v_mov_b32_e32 v27, v193
	v_lshl_add_u64 v[16:17], v[140:141], 1, v[20:21]
	v_mul_f32_e32 v23, v8, v24
	v_mul_f32_e32 v24, v9, v25
	v_mul_f32_e32 v25, v10, v26
	v_mul_f32_e32 v26, v11, v27
	v_cvt_pk_bf16_f32 v24, v23, v24
	v_cvt_pk_bf16_f32 v25, v25, v26
	global_store_dwordx2 v[16:17], v[24:25], off
	v_lshlrev_b64 v[16:17], 9, v[18:19]
	s_cbranch_execz .LBB0_1701
	s_and_b64 vcc, exec, s[4:5]
	s_cbranch_vccnz .LBB0_1704
.LBB0_1695:
	v_ashrrev_i32_e32 v141, 31, v140
	v_lshl_add_u64 v[24:25], v[140:141], 2, s[50:51]
	v_mov_b32_e32 v24, v194
	v_mov_b32_e32 v25, v195
	v_mov_b32_e32 v26, v196
	v_mov_b32_e32 v27, v197
	v_lshl_add_u64 v[20:21], v[140:141], 1, v[20:21]
	v_mul_f32_e32 v23, v12, v24
	v_mul_f32_e32 v24, v13, v25
	v_mul_f32_e32 v25, v14, v26
	v_mul_f32_e32 v26, v15, v27
	v_cvt_pk_bf16_f32 v24, v23, v24
	v_cvt_pk_bf16_f32 v25, v25, v26
	global_store_dwordx2 v[20:21], v[24:25], off offset:32
	s_cbranch_execz .LBB0_1705
	s_and_b64 vcc, exec, s[4:5]
	v_lshlrev_b64 v[18:19], 7, v[18:19]
	s_cbranch_vccnz .LBB0_1708

; DEV unsigned cvt_pk_bf16(float lo, float hi) { unsigned r; asm volatile("v_cvt_pk_bf16_f32 %0, %1, %2" : "=v"(r) : "v"(lo), "v"(hi)); return r; }
;     DEV void operator()(const Acc& acc, const Unit& u, int wr, int wc, int fr, int fq, LAS unsigned char* misc) const {
;     ...
;                     for (int n = 0; n < 2; ++n) { const int c = bj * 128 + wc * 32 + n * 16 + 4 * fq; const f32x4 a = acc[ai][bj][m][n];
;                         if (isq) { sq += (a[0] * a[0] + a[1] * a[1]) + (a[2] * a[2] + a[3] * a[3]);
;                             if (row < TX) { const f32x4 g = *(const f32x4*)(gq + c); u32x2 w; w.x = cvt_pk_bf16(a[0] * g[0], a[1] * g[1]); w.y = cvt_pk_bf16(a[2] * g[2], a[3] * g[3]); *(u32x2*)(aqn + (size_t)row * 256 + c) = w; } }
.LBB0_1701:
	s_and_saveexec_b64 s[46:47], s[10:11]
	s_cbranch_execz .LBB0_1703
	v_ashrrev_i32_e32 v141, 31, v140
	v_lshl_add_u64 v[24:25], v[140:141], 2, s[54:55]
	v_mov_b32_e32 v24, v198
	v_mov_b32_e32 v25, v199
	v_mov_b32_e32 v26, v200
	v_mov_b32_e32 v27, v201
	v_mul_f32_e32 v23, v8, v24
	v_mul_f32_e32 v24, v9, v25
	v_cvt_pk_bf16_f32 v24, v23, v24
	v_mul_f32_e32 v23, v10, v26
	v_mul_f32_e32 v25, v11, v27
	v_lshl_add_u64 v[26:27], s[74:75], 0, v[16:17]
	v_lshl_add_u64 v[26:27], v[140:141], 1, v[26:27]
	v_cvt_pk_bf16_f32 v25, v23, v25
	global_store_dwordx2 v[26:27], v[24:25], off

; DEV unsigned cvt_pk_bf16(float lo, float hi) { unsigned r; asm volatile("v_cvt_pk_bf16_f32 %0, %1, %2" : "=v"(r) : "v"(lo), "v"(hi)); return r; }
;     DEV void operator()(const Acc& acc, const Unit& u, int wr, int wc, int fr, int fq, LAS unsigned char* misc) const {
;     ...
;                     for (int n = 0; n < 2; ++n) { const int c = bj * 128 + wc * 32 + n * 16 + 4 * fq; const f32x4 a = acc[ai][bj][m][n];
;                         if (isq) { sq += (a[0] * a[0] + a[1] * a[1]) + (a[2] * a[2] + a[3] * a[3]);
;                             if (row < TX) { const f32x4 g = *(const f32x4*)(gq + c); u32x2 w; w.x = cvt_pk_bf16(a[0] * g[0], a[1] * g[1]); w.y = cvt_pk_bf16(a[2] * g[2], a[3] * g[3]); *(u32x2*)(aqn + (size_t)row * 256 + c) = w; } }
.LBB0_1704:
.LBB0_1705:
	s_and_saveexec_b64 s[46:47], s[10:11]
	s_cbranch_execz .LBB0_1707
	v_ashrrev_i32_e32 v141, 31, v140
	v_lshl_add_u64 v[20:21], v[140:141], 2, s[54:55]
	v_mov_b32_e32 v24, v202
	v_mov_b32_e32 v25, v203
	v_mov_b32_e32 v26, v204
	v_mov_b32_e32 v27, v205
	v_mul_f32_e32 v20, v12, v24
	v_mul_f32_e32 v21, v13, v25
	v_lshl_add_u64 v[24:25], s[74:75], 0, v[16:17]
	v_cvt_pk_bf16_f32 v20, v20, v21
	v_mul_f32_e32 v21, v14, v26
	v_lshl_add_u64 v[24:25], v[140:141], 1, v[24:25]
	v_mul_f32_e32 v23, v15, v27
	v_cvt_pk_bf16_f32 v21, v21, v23
	global_store_dwordx2 v[24:25], v[20:21], off offset:32

; DEV unsigned cvt_pk_bf16(float lo, float hi) { unsigned r; asm volatile("v_cvt_pk_bf16_f32 %0, %1, %2" : "=v"(r) : "v"(lo), "v"(hi)); return r; }
;     DEV void operator()(const Acc& acc, const Unit& u, int wr, int wc, int fr, int fq, LAS unsigned char* misc) const {
;     ...
;                         if (isq) { sq += (a[0] * a[0] + a[1] * a[1]) + (a[2] * a[2] + a[3] * a[3]);
;                             if (row < TX) { const f32x4 g = *(const f32x4*)(gq + c); u32x2 w; w.x = cvt_pk_bf16(a[0] * g[0], a[1] * g[1]); w.y = cvt_pk_bf16(a[2] * g[2], a[3] * g[3]); *(u32x2*)(aqn + (size_t)row * 256 + c) = w; } }
.LBB0_1709:
	v_mul_f32_e32 v13, v13, v13
	v_mul_f32_e32 v9, v9, v9
	v_fmac_f32_e32 v13, v12, v12
	v_mul_f32_e32 v12, v15, v15
	v_fmac_f32_e32 v9, v8, v8
	v_mul_f32_e32 v8, v11, v11
	v_fmac_f32_e32 v12, v14, v14
	v_fmac_f32_e32 v8, v10, v10
	v_add_f32_e32 v12, v13, v12
	v_add_f32_e32 v8, v9, v8
	s_andn2_b64 vcc, exec, s[46:47]
	v_add_f32_e32 v8, v8, v12
	s_cbranch_vccnz .LBB0_1713
	s_and_saveexec_b64 s[46:47], s[10:11]
	s_cbranch_execz .LBB0_1712
	v_ashrrev_i32_e32 v141, 31, v140
	v_lshl_add_u64 v[10:11], v[140:141], 2, s[54:55]
	v_mov_b32_e32 v10, v206
	v_mov_b32_e32 v11, v207
	v_mov_b32_e32 v12, v208
	v_mov_b32_e32 v13, v209
	v_mul_f32_e32 v9, v4, v10
	v_mul_f32_e32 v10, v5, v11
	v_cvt_pk_bf16_f32 v10, v9, v10
	v_mul_f32_e32 v9, v6, v12
	v_mul_f32_e32 v11, v7, v13
	v_lshl_add_u64 v[12:13], s[74:75], 0, v[16:17]
	v_lshl_add_u64 v[12:13], v[140:141], 1, v[12:13]
	v_cvt_pk_bf16_f32 v11, v9, v11
	global_store_dwordx2 v[12:13], v[10:11], off offset:256

; DEV unsigned cvt_pk_bf16(float lo, float hi) { unsigned r; asm volatile("v_cvt_pk_bf16_f32 %0, %1, %2" : "=v"(r) : "v"(lo), "v"(hi)); return r; }
;     DEV void operator()(const Acc& acc, const Unit& u, int wr, int wc, int fr, int fq, LAS unsigned char* misc) const {
;     ...
;                     for (int n = 0; n < 2; ++n) { const int c = bj * 128 + wc * 32 + n * 16 + 4 * fq; const f32x4 a = acc[ai][bj][m][n];
;                         if (isq) { sq += (a[0] * a[0] + a[1] * a[1]) + (a[2] * a[2] + a[3] * a[3]);
;                             if (row < TX) { const f32x4 g = *(const f32x4*)(gq + c); u32x2 w; w.x = cvt_pk_bf16(a[0] * g[0], a[1] * g[1]); w.y = cvt_pk_bf16(a[2] * g[2], a[3] * g[3]); *(u32x2*)(aqn + (size_t)row * 256 + c) = w; } }
.LBB0_1717:
.LBB0_1718:
	s_and_saveexec_b64 s[4:5], s[10:11]
	s_cbranch_execz .LBB0_1720
	v_ashrrev_i32_e32 v141, 31, v140
	v_lshl_add_u64 v[4:5], v[140:141], 2, s[54:55]
	v_mov_b32_e32 v4, v210
	v_mov_b32_e32 v5, v211
	v_mov_b32_e32 v6, v212
	v_mov_b32_e32 v7, v213
	v_lshl_add_u64 v[10:11], s[74:75], 0, v[16:17]
	v_mul_f32_e32 v4, v0, v4
	v_mul_f32_e32 v5, v1, v5
	v_mul_f32_e32 v6, v2, v6
	v_mul_f32_e32 v7, v3, v7
	v_cvt_pk_bf16_f32 v4, v4, v5
	v_cvt_pk_bf16_f32 v5, v6, v7
	v_lshl_add_u64 v[6:7], v[140:141], 1, v[10:11]
	global_store_dwordx2 v[6:7], v[4:5], off offset:288
